# stack2 + per-segment priority: s_setprio 1 around the PV MFMA cluster of every attention body (8 clusters), s_setprio 0 after it
# speedup vs baseline: 1.0022x; 1.0022x over previous
; template <int MODE> ...
;     ...
;         if (t >= act0 && t < act0 + actn) {
;         const LAS unsigned char* Sl = ring + ((t + base) % 3) * SLOT;
; #pragma unroll
;         for (int hf = 0; hf < NH; ++hf) {
;             if (MODE == 1) { const int ks = ktok0 + 64 * t + 32 * hf;
;                 if (ks + 31 < qtok0 - 128 || ks > qtok0 + 31 + 128) continue; }
;             bf16x8 kf[2][2][2];
; #pragma unroll
;             for (int jj = 0; jj < 2; ++jj)
; #pragma unroll
;                 for (int kt = 0; kt < 2; ++kt)
; #pragma unroll
;                     for (int ks = 0; ks < 2; ++ks) kf[jj][kt][ks] = *(const LAS bf16x8*)(Sl + kad[jj][ks] + (32 * hf + 16 * kt) * 128);
;             f32x4 bb[2][2];
; #pragma unroll
;             for (int jj = 0; jj < 2; ++jj) { const LAS f32x4* bl = bcp + ((MODE == 0) ? (dr0 + t - act0) * 8 : 16 * t + 8 * hf) + bofs[jj];
; #pragma unroll
;                 for (int kt = 0; kt < 2; ++kt) bb[jj][kt] = bl[4 * kt]; }
;             s16x4 vlo[2][4], vhi[2][4];
; #pragma unroll
;             for (int jj = 0; jj < 2; ++jj)
; #pragma unroll
;                 for (int dt = 0; dt < 4; ++dt) { const LAS unsigned char* vp = Sl + vad[jj] + (32 * hf) * 128 + ((dt ^ sv) << 5);
;                     vlo[jj][dt] = __builtin_bit_cast(s16x4, __builtin_amdgcn_ds_read_tr16_b64_v4i16((LAS s16x4*)(vp)));
;                     vhi[jj][dt] = __builtin_bit_cast(s16x4, __builtin_amdgcn_ds_read_tr16_b64_v4i16((LAS s16x4*)(vp + 2048))); }
;             __builtin_amdgcn_sched_barrier(0);
;             f32x4 s[2][2];
; #pragma unroll
;             for (int jj = 0; jj < 2; ++jj)
; #pragma unroll
;                 for (int kt = 0; kt < 2; ++kt) { f32x4 a = (MODE == 0) ? bb[jj][kt] + mneg[jj][kt] : bb[jj][kt];
;                     a = __builtin_amdgcn_mfma_f32_16x16x32_bf16(kf[jj][kt][0], qf[jj][0], a, 0, 0, 0);
;                     s[jj][kt] = __builtin_amdgcn_mfma_f32_16x16x32_bf16(kf[jj][kt][1], qf[jj][1], a, 0, 0, 0); }
;             u32x4 pw[2];
; #pragma unroll
;             for (int jj = 0; jj < 2; ++jj) {
;                 const float tm = vmax3(vmax3(s[jj][0][0], s[jj][0][1], s[jj][0][2]), vmax3(s[jj][0][3], s[jj][1][0], s[jj][1][1]), vmax3(s[jj][1][2], s[jj][1][3], s[jj][1][3]));
;                 const float mn = quad_max3(mrun[jj], tm);
;                 const float alpha = __builtin_amdgcn_exp2f(mrun[jj] - mn);
;                 mrun[jj] = mn;
.LBB0_278:
	s_sub_i32 s52, s25, s23
	v_lshlrev_b32_e32 v94, 5, v93
	s_add_i32 s0, s23, 7
	v_xor_b32_e32 v95, 32, v94
	v_xor_b32_e32 v96, 64, v94
	s_cmp_gt_u32 s0, 7
	v_xor_b32_e32 v97, 0x60, v94
	s_cbranch_scc1 .LBB0_291
	s_lshl_b32 s0, s86, 14
	s_add_i32 s0, s0, 0
	v_add_u32_e32 v0, s0, v89
	s_lshl_b32 s14, s52, 7
	v_add_u32_e32 v2, s0, v88
	ds_read_b128 v[6:9], v0
	ds_read_b128 v[10:13], v0 offset:2048
	ds_read_b128 v[14:17], v2
	ds_read_b128 v[34:37], v2 offset:2048
	v_add_u32_e32 v0, s0, v92
	s_add_i32 s14, s24, s14
	v_add_u32_e32 v2, s0, v91
	ds_read_b128 v[38:41], v0
	ds_read_b128 v[42:45], v0 offset:2048
	ds_read_b128 v[46:49], v2
	ds_read_b128 v[50:53], v2 offset:2048
	v_lshl_add_u32 v0, v87, 4, s14
	ds_read_b128 v[54:57], v0
	ds_read_b128 v[58:61], v0 offset:64
	v_lshl_add_u32 v0, v90, 4, s14
	ds_read_b128 v[62:65], v0
	ds_read_b128 v[66:69], v0 offset:64
	v_add3_u32 v0, v86, v122, s0
	v_add_u32_e32 v2, v0, v94
	v_add_u32_e32 v3, v0, v95
	ds_read_b64_tr_b16 v[70:71], v2 offset:8192
	ds_read_b64_tr_b16 v[72:73], v2 offset:10240
	ds_read_b64_tr_b16 v[74:75], v3 offset:8192
	ds_read_b64_tr_b16 v[76:77], v3 offset:10240
	v_add_u32_e32 v2, v0, v96
	v_add_u32_e32 v0, v0, v97
	ds_read_b64_tr_b16 v[78:79], v2 offset:8192
	ds_read_b64_tr_b16 v[80:81], v2 offset:10240
	ds_read_b64_tr_b16 v[126:127], v0 offset:8192
	ds_read_b64_tr_b16 v[128:129], v0 offset:10240
	v_add3_u32 v0, v123, v122, s0
	v_add_u32_e32 v2, v0, v94
	v_add_u32_e32 v3, v0, v95
	ds_read_b64_tr_b16 v[130:131], v2 offset:8192
	ds_read_b64_tr_b16 v[132:133], v2 offset:10240
	ds_read_b64_tr_b16 v[134:135], v3 offset:8192
	ds_read_b64_tr_b16 v[136:137], v3 offset:10240
	v_add_u32_e32 v2, v0, v96
	v_add_u32_e32 v0, v0, v97
	ds_read_b64_tr_b16 v[138:139], v2 offset:8192
	ds_read_b64_tr_b16 v[140:141], v2 offset:10240
	ds_read_b64_tr_b16 v[2:3], v0 offset:8192
	ds_read_b64_tr_b16 v[4:5], v0 offset:10240
	s_waitcnt lgkmcnt(14)
	v_pk_add_f32 v[56:57], v[112:113], v[56:57]
	v_pk_add_f32 v[54:55], v[110:111], v[54:55]
	s_mov_b32 s0, 0xf149f2ca
	s_nop 0
	v_mfma_f32_16x16x32_bf16 v[6:9], v[6:9], v[30:33], v[54:57]
	s_nop 2
	v_pk_add_f32 v[56:57], v[114:115], v[60:61]
	v_pk_add_f32 v[54:55], v[108:109], v[58:59]
	v_mfma_f32_16x16x32_bf16 v[6:9], v[14:17], v[26:29], v[6:9]
	v_pk_add_f32 v[16:17], v[106:107], v[64:65]
	v_pk_add_f32 v[14:15], v[102:103], v[62:63]
	v_mfma_f32_16x16x32_bf16 v[10:13], v[10:13], v[30:33], v[54:57]
	v_mfma_f32_16x16x32_bf16 v[10:13], v[34:37], v[26:29], v[10:13]
	s_nop 2
	v_maximum3_f32 v0, v6, v7, v8
	v_pk_add_f32 v[56:57], v[104:105], v[68:69]
	v_pk_add_f32 v[54:55], v[100:101], v[66:67]
	v_mfma_f32_16x16x32_bf16 v[14:17], v[38:41], v[22:25], v[14:17]
	v_mfma_f32_16x16x32_bf16 v[14:17], v[46:49], v[18:21], v[14:17]
	v_maximum3_f32 v34, v9, v10, v11
	v_maximum3_f32 v35, v12, v13, v13
	v_maximum3_f32 v0, v0, v34, v35
	v_mov_b32_e32 v34, v0
	s_nop 1
	v_permlane16_swap_b32_e32 v0, v34
	v_maximum3_f32 v0, v0, v34, v34
	v_mov_b32_e32 v34, v0
	s_nop 1
	v_permlane32_swap_b32_e32 v0, v34
	v_maximum3_f32 v125, v0, s0, v34
	v_mfma_f32_16x16x32_bf16 v[34:37], v[42:45], v[22:25], v[54:57]
	v_sub_f32_e32 v6, v6, v125
	v_exp_f32_e32 v38, v6
	v_sub_f32_e32 v6, v7, v125
	v_mfma_f32_16x16x32_bf16 v[34:37], v[50:53], v[18:21], v[34:37]
	v_exp_f32_e32 v40, v6
	v_sub_f32_e32 v6, v8, v125
	v_exp_f32_e32 v42, v6
	v_sub_f32_e32 v6, v9, v125
	v_sub_f32_e32 v0, 0xf149f2ca, v125
	v_exp_f32_e32 v66, v6
	v_sub_f32_e32 v6, v10, v125
	v_exp_f32_e32 v68, v6
	v_sub_f32_e32 v6, v11, v125
	v_exp_f32_e32 v146, v0
	v_maximum3_f32 v0, v14, v15, v16
	v_maximum3_f32 v10, v17, v34, v35
	v_maximum3_f32 v11, v36, v37, v37
	v_maximum3_f32 v0, v0, v10, v11
	v_mov_b32_e32 v10, v0
	s_nop 1
	v_permlane16_swap_b32_e32 v0, v10
	v_maximum3_f32 v0, v0, v10, v10
	v_mov_b32_e32 v10, v0
	s_nop 1
	v_permlane32_swap_b32_e32 v0, v10
	v_maximum3_f32 v124, v0, s0, v10
	v_exp_f32_e32 v98, v6
	v_sub_f32_e32 v6, v12, v125
	v_sub_f32_e32 v0, 0xf149f2ca, v124
	v_exp_f32_e32 v142, v6
	v_sub_f32_e32 v6, v13, v125
	v_sub_f32_e32 v10, v14, v124
	v_exp_f32_e32 v147, v0
	v_exp_f32_e32 v144, v6
	v_exp_f32_e32 v39, v10
	v_sub_f32_e32 v10, v15, v124
	v_exp_f32_e32 v41, v10
	v_sub_f32_e32 v10, v16, v124
	v_sub_f32_e32 v0, v34, v124
	v_exp_f32_e32 v43, v10
	v_sub_f32_e32 v10, v17, v124
	v_exp_f32_e32 v69, v0
	v_sub_f32_e32 v0, v35, v124
	v_exp_f32_e32 v67, v10
	v_pk_mul_f32 v[10:11], v[146:147], 0 op_sel_hi:[1,0]
	v_exp_f32_e32 v99, v0
	v_sub_f32_e32 v0, v36, v124
	v_cvt_pk_bf16_f32 v6, v38, v40
	v_cvt_pk_bf16_f32 v7, v42, v66
	v_cvt_pk_bf16_f32 v8, v68, v98
	v_cvt_pk_bf16_f32 v9, v142, v144
	v_mov_b32_e32 v14, v10
	v_mov_b32_e32 v15, v10
	v_mov_b32_e32 v16, v10
	v_mov_b32_e32 v17, v10
	v_exp_f32_e32 v143, v0
	v_sub_f32_e32 v0, v37, v124
	v_mfma_f32_16x16x32_bf16 v[54:57], v[70:73], v[6:9], v[14:17]
	v_exp_f32_e32 v145, v0
	v_mov_b32_e32 v10, v11
	v_mov_b32_e32 v12, v11
	s_setprio 1
	s_waitcnt lgkmcnt(12)
	v_mfma_f32_16x16x32_bf16 v[62:65], v[74:77], v[6:9], v[14:17]
	v_mov_b32_e32 v13, v11
	v_cvt_pk_bf16_f32 v34, v39, v41
	v_cvt_pk_bf16_f32 v35, v43, v67
	s_waitcnt lgkmcnt(10)
	v_mfma_f32_16x16x32_bf16 v[58:61], v[78:81], v[6:9], v[14:17]
	v_cvt_pk_bf16_f32 v36, v69, v99
	v_cvt_pk_bf16_f32 v37, v143, v145
	s_waitcnt lgkmcnt(8)
	v_mfma_f32_16x16x32_bf16 v[50:53], v[126:129], v[6:9], v[14:17]
	v_add_f32_e64 v6, v38, 0
	v_add_f32_e64 v7, v39, 0
	v_pk_add_f32 v[6:7], v[40:41], v[6:7]
	s_waitcnt lgkmcnt(6)
	v_mfma_f32_16x16x32_bf16 v[46:49], v[130:133], v[34:37], v[10:13]
	v_pk_add_f32 v[6:7], v[42:43], v[6:7]
	v_pk_add_f32 v[6:7], v[66:67], v[6:7]
	s_waitcnt lgkmcnt(4)
	v_mfma_f32_16x16x32_bf16 v[42:45], v[134:137], v[34:37], v[10:13]
	v_pk_add_f32 v[6:7], v[68:69], v[6:7]
	v_pk_add_f32 v[6:7], v[98:99], v[6:7]
	s_waitcnt lgkmcnt(2)
	v_mfma_f32_16x16x32_bf16 v[38:41], v[138:141], v[34:37], v[10:13]
	v_pk_add_f32 v[6:7], v[142:143], v[6:7]
	v_pk_add_f32 v[6:7], v[144:145], v[6:7]
	s_waitcnt lgkmcnt(0)
	v_mfma_f32_16x16x32_bf16 v[34:37], v[2:5], v[34:37], v[10:13]
	s_setprio 0
	v_fma_f32 v98, v146, 0, v6
	v_fma_f32 v99, v147, 0, v7
	s_cmp_eq_u32 s41, 1
	s_cbranch_scc1 .LBB0_281
	s_branch .LBB0_292

; #define LAS __attribute__((address_space(3)))
; #define GAS __attribute__((address_space(1)))
; template <int MODE> ...
;     ...
;         if (t >= act0 && t < act0 + actn) {
;         const LAS unsigned char* Sl = ring + ((t + base) % 3) * SLOT;
; #pragma unroll
;         for (int hf = 0; hf < NH; ++hf) {
;             if (MODE == 1) { const int ks = ktok0 + 64 * t + 32 * hf;
;                 if (ks + 31 < qtok0 - 128 || ks > qtok0 + 31 + 128) continue; }
;             bf16x8 kf[2][2][2];
; #pragma unroll
;             for (int jj = 0; jj < 2; ++jj)
; #pragma unroll
;                 for (int kt = 0; kt < 2; ++kt)
; #pragma unroll
;                     for (int ks = 0; ks < 2; ++ks) kf[jj][kt][ks] = *(const LAS bf16x8*)(Sl + kad[jj][ks] + (32 * hf + 16 * kt) * 128);
;             f32x4 bb[2][2];
; #pragma unroll
;             for (int jj = 0; jj < 2; ++jj) { const LAS f32x4* bl = bcp + ((MODE == 0) ? (dr0 + t - act0) * 8 : 16 * t + 8 * hf) + bofs[jj];
; #pragma unroll
;                 for (int kt = 0; kt < 2; ++kt) bb[jj][kt] = bl[4 * kt]; }
;             s16x4 vlo[2][4], vhi[2][4];
; #pragma unroll
;             for (int jj = 0; jj < 2; ++jj)
; #pragma unroll
;                 for (int dt = 0; dt < 4; ++dt) { const LAS unsigned char* vp = Sl + vad[jj] + (32 * hf) * 128 + ((dt ^ sv) << 5);
;                     vlo[jj][dt] = __builtin_bit_cast(s16x4, __builtin_amdgcn_ds_read_tr16_b64_v4i16((LAS s16x4*)(vp)));
;                     vhi[jj][dt] = __builtin_bit_cast(s16x4, __builtin_amdgcn_ds_read_tr16_b64_v4i16((LAS s16x4*)(vp + 2048))); }
;             __builtin_amdgcn_sched_barrier(0);
;     ...
;     for (int t = 0; t < nT - 1; ++t) { head(t); body(t); }
;     head(nT - 1);
;     bf16x8 qn[2][2];
;     { const GAS bf16_t* qs = nQ ? (const GAS bf16_t*)nQ : (const GAS bf16_t*)proj + (size_t)qtok0 * NIN + qcol;
; #pragma unroll
;       for (int jj = 0; jj < 2; ++jj)
; #pragma unroll
;           for (int ks = 0; ks < 2; ++ks) qn[jj][ks] = *(const GAS bf16x8*)(qs + (size_t)(16 * jj) * NIN + 32 * ks + qoff); }
;     body(nT - 1);
.LBB0_283:
	s_add_i32 s42, s86, s26
	s_add_i32 s0, s42, 1
	s_mul_hi_i32 s14, s0, 0x55555556
	s_lshr_b32 s15, s14, 31
	s_add_i32 s14, s14, s15
	s_mul_i32 s14, s14, 3
	s_sub_i32 s0, s0, s14
	s_lshl_b32 s0, s0, 14
	s_add_i32 s0, s0, s94
	s_add_u32 s34, s34, 0x48000
	s_addc_u32 s35, s35, 0
	s_add_u32 s30, s30, 0x48000
	s_barrier
	s_addc_u32 s31, s31, 0
	s_mov_b32 m0, s0
	s_nop 0
	global_load_lds_dwordx4 v84, s[34:35]
	s_add_u32 m0, m0, 0x2000
	s_nop 0
	global_load_lds_dwordx4 v85, s[30:31]
	v_lshl_add_u64 v[6:7], v[82:83], 1, s[38:39]
	global_load_dwordx4 v[2:5], v[6:7], off
	global_load_dwordx4 v[10:13], v[6:7], off offset:64
	v_add_co_u32_e32 v6, vcc, 0x12000, v6
	s_cmp_gt_u32 s40, s27
	s_nop 0
	v_addc_co_u32_e32 v7, vcc, 0, v7, vcc
	global_load_dwordx4 v[14:17], v[6:7], off
	s_nop 0
	global_load_dwordx4 v[6:9], v[6:7], off offset:64
	s_cselect_b64 s[30:31], -1, 0
	s_add_i32 s0, s23, 8
	s_cmp_le_i32 s26, s0
	s_cselect_b64 s[26:27], -1, 0
	s_and_b64 s[26:27], s[30:31], s[26:27]
	s_and_b64 vcc, exec, s[26:27]
	s_cbranch_vccz .LBB0_285
	s_add_i32 s0, s41, s86
	s_mul_hi_i32 s14, s0, 0x55555556
	s_lshr_b32 s15, s14, 31
	s_add_i32 s14, s14, s15
	s_mul_i32 s14, s14, 3
	s_sub_i32 s0, s0, s14
	s_lshl_b32 s0, s0, 14
	s_sub_i32 s14, s41, s23
	s_add_i32 s0, s0, 0
	s_add_i32 s14, s14, s25
	v_add_u32_e32 v0, s0, v89
	s_lshl_b32 s14, s14, 7
	v_add_u32_e32 v66, s0, v88
	ds_read_b128 v[126:129], v0
	ds_read_b128 v[130:133], v0 offset:2048
	ds_read_b128 v[134:137], v66
	ds_read_b128 v[138:141], v66 offset:2048
	v_add_u32_e32 v0, s0, v92
	s_add_i32 s24, s24, s14
	v_add_u32_e32 v66, s0, v91
	ds_read_b128 v[142:145], v0
	ds_read_b128 v[146:149], v0 offset:2048
	ds_read_b128 v[150:153], v66
	ds_read_b128 v[154:157], v66 offset:2048
	v_lshl_add_u32 v0, v87, 4, s24
	ds_read_b128 v[158:161], v0
	ds_read_b128 v[162:165], v0 offset:64
	v_lshl_add_u32 v0, v90, 4, s24
	ds_read_b128 v[166:169], v0
	ds_read_b128 v[170:173], v0 offset:64
	v_lshlrev_b32_e32 v0, 5, v93
	v_add3_u32 v66, v86, v122, s0
	v_add_u32_e32 v67, v66, v0
	v_xor_b32_e32 v68, 32, v0
	v_add_u32_e32 v69, v66, v68
	ds_read_b64_tr_b16 v[94:95], v67 offset:8192
	ds_read_b64_tr_b16 v[96:97], v67 offset:10240
	ds_read_b64_tr_b16 v[90:91], v69 offset:8192
	ds_read_b64_tr_b16 v[92:93], v69 offset:10240
	v_xor_b32_e32 v67, 64, v0
	v_xor_b32_e32 v70, 0x60, v0
	v_add_u32_e32 v69, v66, v67
	v_add_u32_e32 v66, v66, v70
	ds_read_b64_tr_b16 v[86:87], v69 offset:8192
	ds_read_b64_tr_b16 v[88:89], v69 offset:10240
	ds_read_b64_tr_b16 v[82:83], v66 offset:8192
	ds_read_b64_tr_b16 v[84:85], v66 offset:10240
	v_add3_u32 v66, v123, v122, s0
	v_add_u32_e32 v0, v66, v0
	v_add_u32_e32 v68, v66, v68
	ds_read_b64_tr_b16 v[78:79], v0 offset:8192
	ds_read_b64_tr_b16 v[80:81], v0 offset:10240
	ds_read_b64_tr_b16 v[74:75], v68 offset:8192
	ds_read_b64_tr_b16 v[76:77], v68 offset:10240
	v_add_u32_e32 v0, v66, v67
	v_add_u32_e32 v68, v66, v70
	ds_read_b64_tr_b16 v[70:71], v0 offset:8192
	ds_read_b64_tr_b16 v[72:73], v0 offset:10240
	ds_read_b64_tr_b16 v[66:67], v68 offset:8192
	ds_read_b64_tr_b16 v[68:69], v68 offset:10240
	s_waitcnt lgkmcnt(14)
; __device__ __forceinline__ unsigned cvtpk(float lo, float hi) { f32x2 v = {lo, hi}; bf16x2_t b = __builtin_convertvector(v, bf16x2_t); return __builtin_bit_cast(unsigned, b); }
; __device__ __forceinline__ float vmax3(float a, float b, float c) { return __builtin_elementwise_maximum(__builtin_elementwise_maximum(a, b), c); }
; template <int MODE> ...
;     ...
;             f32x4 s[2][2];
; #pragma unroll
;             for (int jj = 0; jj < 2; ++jj)
; #pragma unroll
;                 for (int kt = 0; kt < 2; ++kt) { f32x4 a = (MODE == 0) ? bb[jj][kt] + mneg[jj][kt] : bb[jj][kt];
;                     a = __builtin_amdgcn_mfma_f32_16x16x32_bf16(kf[jj][kt][0], qf[jj][0], a, 0, 0, 0);
;                     s[jj][kt] = __builtin_amdgcn_mfma_f32_16x16x32_bf16(kf[jj][kt][1], qf[jj][1], a, 0, 0, 0); }
;             u32x4 pw[2];
; #pragma unroll
;             for (int jj = 0; jj < 2; ++jj) {
;                 const float tm = vmax3(vmax3(s[jj][0][0], s[jj][0][1], s[jj][0][2]), vmax3(s[jj][0][3], s[jj][1][0], s[jj][1][1]), vmax3(s[jj][1][2], s[jj][1][3], s[jj][1][3]));
;                 const float mn = quad_max3(mrun[jj], tm);
;                 const float alpha = __builtin_amdgcn_exp2f(mrun[jj] - mn);
;                 mrun[jj] = mn;
;                 float rsum = 0.f;
; #pragma unroll
;                 for (int kt = 0; kt < 2; ++kt)
; #pragma unroll
;                     for (int e = 0; e < 4; ++e) { s[jj][kt][e] = __builtin_amdgcn_exp2f(s[jj][kt][e] - mn); rsum += s[jj][kt][e]; }
;                 lrun[jj] = lrun[jj] * alpha + rsum;
; #pragma unroll
;                 for (int dt = 0; dt < 4; ++dt) o[jj][dt] *= alpha;
;                 pw[jj].x = cvtpk(s[jj][0][0], s[jj][0][1]); pw[jj].y = cvtpk(s[jj][0][2], s[jj][0][3]); pw[jj].z = cvtpk(s[jj][1][0], s[jj][1][1]); pw[jj].w = cvtpk(s[jj][1][2], s[jj][1][3]);
;             }
; #pragma unroll
;             for (int jj = 0; jj < 2; ++jj)
; #pragma unroll
;                 for (int dt = 0; dt < 4; ++dt) {
;                     const bf16x8 vf = (bf16x8){vlo[jj][dt][0], vlo[jj][dt][1], vlo[jj][dt][2], vlo[jj][dt][3], vhi[jj][dt][0], vhi[jj][dt][1], vhi[jj][dt][2], vhi[jj][dt][3]};
;                     o[jj][dt] = __builtin_amdgcn_mfma_f32_16x16x32_bf16(vf, __builtin_bit_cast(bf16x8, pw[jj]), o[jj][dt], 0, 0, 0); }
;             __builtin_amdgcn_sched_barrier(0);
	v_pk_add_f32 v[112:113], v[112:113], v[160:161]
	v_pk_add_f32 v[110:111], v[110:111], v[158:159]
	v_pk_add_f32 v[114:115], v[114:115], v[164:165]
	v_pk_add_f32 v[100:101], v[100:101], v[170:171]
	v_mfma_f32_16x16x32_bf16 v[110:113], v[126:129], v[30:33], v[110:113]
	v_mfma_f32_16x16x32_bf16 v[126:129], v[134:137], v[26:29], v[110:113]
	s_nop 6
	v_pk_add_f32 v[112:113], v[108:109], v[162:163]
	v_maximum3_f32 v0, v126, v127, v128
	v_pk_add_f32 v[108:109], v[106:107], v[168:169]
	v_mfma_f32_16x16x32_bf16 v[30:33], v[130:133], v[30:33], v[112:115]
	v_pk_add_f32 v[106:107], v[102:103], v[166:167]
	v_pk_add_f32 v[102:103], v[104:105], v[172:173]
	v_mfma_f32_16x16x32_bf16 v[26:29], v[138:141], v[26:29], v[30:33]
	s_nop 7
	v_maximum3_f32 v30, v129, v26, v27
	v_maximum3_f32 v31, v28, v29, v29
	v_maximum3_f32 v0, v0, v30, v31
	v_mov_b32_e32 v104, v0
	s_nop 1
	v_permlane16_swap_b32_e32 v0, v104
	v_mfma_f32_16x16x32_bf16 v[30:33], v[142:145], v[22:25], v[106:109]
	v_maximum3_f32 v0, v0, v104, v104
	v_mov_b32_e32 v104, v0
	s_nop 1
	v_permlane32_swap_b32_e32 v0, v104
	v_mfma_f32_16x16x32_bf16 v[22:25], v[146:149], v[22:25], v[100:103]
	v_maximum3_f32 v0, v125, v0, v104
	v_mfma_f32_16x16x32_bf16 v[30:33], v[150:153], v[18:21], v[30:33]
	s_nop 0
	v_sub_f32_e32 v100, v125, v0
	v_exp_f32_e32 v122, v100
	v_sub_f32_e32 v101, v126, v0
	v_mfma_f32_16x16x32_bf16 v[18:21], v[154:157], v[18:21], v[22:25]
	v_exp_f32_e32 v104, v101
	v_pk_mul_f32 v[60:61], v[60:61], v[122:123] op_sel_hi:[1,0]
	v_pk_mul_f32 v[58:59], v[58:59], v[122:123] op_sel_hi:[1,0]
	v_sub_f32_e32 v22, v127, v0
	v_exp_f32_e32 v106, v22
	v_sub_f32_e32 v22, v128, v0
	v_exp_f32_e32 v108, v22
	v_sub_f32_e32 v22, v129, v0
	v_exp_f32_e32 v110, v22
	v_sub_f32_e32 v22, v26, v0
	v_exp_f32_e32 v112, v22
	v_sub_f32_e32 v22, v27, v0
	v_exp_f32_e32 v114, v22
	v_sub_f32_e32 v22, v28, v0
	v_sub_f32_e32 v0, v29, v0
	v_exp_f32_e32 v126, v22
	v_exp_f32_e32 v128, v0
	v_pk_mul_f32 v[22:23], v[54:55], v[122:123] op_sel_hi:[1,0]
	v_maximum3_f32 v0, v30, v31, v32
	v_maximum3_f32 v54, v33, v18, v19
	v_maximum3_f32 v55, v20, v21, v21
	v_maximum3_f32 v0, v0, v54, v55
	v_mov_b32_e32 v54, v0
	s_nop 1
	v_permlane16_swap_b32_e32 v0, v54
	v_maximum3_f32 v0, v0, v54, v54
	v_mov_b32_e32 v54, v0
	s_nop 1
	v_permlane32_swap_b32_e32 v0, v54
	v_maximum3_f32 v0, v124, v0, v54
	v_sub_f32_e32 v30, v30, v0
	v_exp_f32_e32 v105, v30
	v_sub_f32_e32 v30, v31, v0
	v_exp_f32_e32 v107, v30
	v_sub_f32_e32 v30, v32, v0
	v_sub_f32_e32 v18, v18, v0
	v_exp_f32_e32 v109, v30
	v_sub_f32_e32 v30, v33, v0
	v_exp_f32_e32 v113, v18
	v_sub_f32_e32 v18, v19, v0
	v_sub_f32_e32 v54, v124, v0
	v_exp_f32_e32 v111, v30
	v_exp_f32_e32 v115, v18
	v_sub_f32_e32 v18, v20, v0
	v_pk_mul_f32 v[24:25], v[56:57], v[122:123] op_sel_hi:[1,0]
	v_pk_mul_f32 v[28:29], v[64:65], v[122:123] op_sel_hi:[1,0]
	v_pk_mul_f32 v[26:27], v[62:63], v[122:123] op_sel_hi:[1,0]
	v_pk_mul_f32 v[52:53], v[52:53], v[122:123] op_sel_hi:[1,0]
	v_pk_mul_f32 v[50:51], v[50:51], v[122:123] op_sel_hi:[1,0]
	v_exp_f32_e32 v127, v18
	v_sub_f32_e32 v0, v21, v0
	v_exp_f32_e32 v123, v54
	v_pk_add_f32 v[18:19], v[104:105], 0 op_sel_hi:[1,0]
	v_exp_f32_e32 v129, v0
	v_pk_add_f32 v[18:19], v[106:107], v[18:19]
	v_cvt_pk_bf16_f32 v100, v104, v106
	v_pk_add_f32 v[18:19], v[108:109], v[18:19]
	v_cvt_pk_bf16_f32 v101, v108, v110
	v_pk_add_f32 v[18:19], v[110:111], v[18:19]
	v_cvt_pk_bf16_f32 v102, v112, v114
	v_cvt_pk_bf16_f32 v103, v126, v128
	v_pk_add_f32 v[18:19], v[112:113], v[18:19]
	v_mov_b32_e32 v0, v123
	v_mfma_f32_16x16x32_bf16 v[54:57], v[94:97], v[100:103], v[22:25]
	v_pk_mul_f32 v[20:21], v[48:49], v[0:1] op_sel_hi:[1,0]
	s_setprio 1
	s_waitcnt lgkmcnt(12)
	v_mfma_f32_16x16x32_bf16 v[62:65], v[90:93], v[100:103], v[26:29]
	v_cvt_pk_bf16_f32 v22, v105, v107
	v_cvt_pk_bf16_f32 v23, v109, v111
	v_cvt_pk_bf16_f32 v24, v113, v115
	v_pk_add_f32 v[26:27], v[114:115], v[18:19]
	v_pk_mul_f32 v[18:19], v[46:47], v[0:1] op_sel_hi:[1,0]
	v_cvt_pk_bf16_f32 v25, v127, v129
	s_waitcnt lgkmcnt(10)
	v_mfma_f32_16x16x32_bf16 v[58:61], v[86:89], v[100:103], v[58:61]
	v_pk_add_f32 v[26:27], v[126:127], v[26:27]
	v_pk_add_f32 v[26:27], v[128:129], v[26:27]
	s_waitcnt lgkmcnt(6)
	v_mfma_f32_16x16x32_bf16 v[46:49], v[78:81], v[22:25], v[18:21]
	v_fma_f32 v98, v98, v122, v26
	v_fma_f32 v99, v99, v123, v27
	s_nop 0
	v_pk_mul_f32 v[20:21], v[44:45], v[0:1] op_sel_hi:[1,0]
	v_pk_mul_f32 v[18:19], v[42:43], v[0:1] op_sel_hi:[1,0]
	v_mfma_f32_16x16x32_bf16 v[50:53], v[82:85], v[100:103], v[50:53]
	s_waitcnt lgkmcnt(4)
	v_mfma_f32_16x16x32_bf16 v[42:45], v[74:77], v[22:25], v[18:21]
	s_nop 2
	v_pk_mul_f32 v[20:21], v[40:41], v[0:1] op_sel_hi:[1,0]
	v_pk_mul_f32 v[18:19], v[38:39], v[0:1] op_sel_hi:[1,0]
	s_waitcnt lgkmcnt(2)
	s_nop 0
	v_mfma_f32_16x16x32_bf16 v[38:41], v[70:73], v[22:25], v[18:21]
	s_nop 2
	v_pk_mul_f32 v[20:21], v[36:37], v[0:1] op_sel_hi:[1,0]
	v_pk_mul_f32 v[18:19], v[34:35], v[0:1] op_sel_hi:[1,0]
	s_waitcnt lgkmcnt(0)
	s_setprio 0
	s_nop 0
	v_mfma_f32_16x16x32_bf16 v[34:37], v[66:69], v[22:25], v[18:21]

; #define LAS __attribute__((address_space(3)))
; template <int MODE> ...
;     ...
;         const LAS unsigned char* Sl = ring + ((t + base) % 3) * SLOT;
; #pragma unroll
;         for (int hf = 0; hf < NH; ++hf) {
;             if (MODE == 1) { const int ks = ktok0 + 64 * t + 32 * hf;
;                 if (ks + 31 < qtok0 - 128 || ks > qtok0 + 31 + 128) continue; }
;             bf16x8 kf[2][2][2];
; #pragma unroll
;             for (int jj = 0; jj < 2; ++jj)
; #pragma unroll
;                 for (int kt = 0; kt < 2; ++kt)
; #pragma unroll
;                     for (int ks = 0; ks < 2; ++ks) kf[jj][kt][ks] = *(const LAS bf16x8*)(Sl + kad[jj][ks] + (32 * hf + 16 * kt) * 128);
;             f32x4 bb[2][2];
; #pragma unroll
;             for (int jj = 0; jj < 2; ++jj) { const LAS f32x4* bl = bcp + ((MODE == 0) ? (dr0 + t - act0) * 8 : 16 * t + 8 * hf) + bofs[jj];
; #pragma unroll
;                 for (int kt = 0; kt < 2; ++kt) bb[jj][kt] = bl[4 * kt]; }
;             s16x4 vlo[2][4], vhi[2][4];
; #pragma unroll
;             for (int jj = 0; jj < 2; ++jj)
; #pragma unroll
;                 for (int dt = 0; dt < 4; ++dt) { const LAS unsigned char* vp = Sl + vad[jj] + (32 * hf) * 128 + ((dt ^ sv) << 5);
;                     vlo[jj][dt] = __builtin_bit_cast(s16x4, __builtin_amdgcn_ds_read_tr16_b64_v4i16((LAS s16x4*)(vp)));
;                     vhi[jj][dt] = __builtin_bit_cast(s16x4, __builtin_amdgcn_ds_read_tr16_b64_v4i16((LAS s16x4*)(vp + 2048))); }
;             __builtin_amdgcn_sched_barrier(0);
.LBB0_298:
	s_add_i32 s0, s86, 1
	s_mul_hi_i32 s14, s0, 0x55555556
	s_lshr_b32 s15, s14, 31
	s_add_i32 s14, s14, s15
	s_mul_i32 s14, s14, 3
	s_sub_i32 s0, s0, s14
	s_lshl_b32 s0, s0, 14
	s_add_i32 s0, s0, 0
	v_add_u32_e32 v0, s0, v89
	s_lshl_b32 s14, s52, 7
	v_add_u32_e32 v2, s0, v88
	ds_read_b128 v[126:129], v0
	ds_read_b128 v[130:133], v0 offset:2048
	ds_read_b128 v[134:137], v2
	ds_read_b128 v[138:141], v2 offset:2048
	v_add_u32_e32 v0, s0, v92
	s_add_i32 s14, s24, s14
	v_add_u32_e32 v2, s0, v91
	ds_read_b128 v[142:145], v0
	ds_read_b128 v[146:149], v0 offset:2048
	ds_read_b128 v[150:153], v2
	ds_read_b128 v[154:157], v2 offset:2048
	v_lshl_add_u32 v0, v87, 4, s14
	ds_read_b128 v[158:161], v0 offset:128
	ds_read_b128 v[162:165], v0 offset:192
	v_lshl_add_u32 v0, v90, 4, s14
	ds_read_b128 v[166:169], v0 offset:128
	ds_read_b128 v[170:173], v0 offset:192
	v_add3_u32 v0, v86, v122, s0
	v_add_u32_e32 v2, v0, v94
	v_add_u32_e32 v3, v0, v95
	ds_read_b64_tr_b16 v[78:79], v2 offset:8192
	ds_read_b64_tr_b16 v[80:81], v2 offset:10240
	ds_read_b64_tr_b16 v[74:75], v3 offset:8192
	ds_read_b64_tr_b16 v[76:77], v3 offset:10240
	v_add_u32_e32 v2, v0, v96
	v_add_u32_e32 v0, v0, v97
	ds_read_b64_tr_b16 v[70:71], v2 offset:8192
	ds_read_b64_tr_b16 v[72:73], v2 offset:10240
	ds_read_b64_tr_b16 v[66:67], v0 offset:8192
	ds_read_b64_tr_b16 v[68:69], v0 offset:10240
	v_add3_u32 v0, v123, v122, s0
	v_add_u32_e32 v2, v0, v94
	v_add_u32_e32 v3, v0, v95
	ds_read_b64_tr_b16 v[14:15], v2 offset:8192
	ds_read_b64_tr_b16 v[16:17], v2 offset:10240
	ds_read_b64_tr_b16 v[10:11], v3 offset:8192
	ds_read_b64_tr_b16 v[12:13], v3 offset:10240
	v_add_u32_e32 v2, v0, v96
	v_add_u32_e32 v0, v0, v97
	ds_read_b64_tr_b16 v[6:7], v2 offset:8192
	ds_read_b64_tr_b16 v[8:9], v2 offset:10240
	ds_read_b64_tr_b16 v[2:3], v0 offset:8192
	ds_read_b64_tr_b16 v[4:5], v0 offset:10240
	s_waitcnt lgkmcnt(14)
; __device__ __forceinline__ unsigned cvtpk(float lo, float hi) { f32x2 v = {lo, hi}; bf16x2_t b = __builtin_convertvector(v, bf16x2_t); return __builtin_bit_cast(unsigned, b); }
; __device__ __forceinline__ float vmax3(float a, float b, float c) { return __builtin_elementwise_maximum(__builtin_elementwise_maximum(a, b), c); }
; template <int MODE> ...
;     ...
;             f32x4 s[2][2];
; #pragma unroll
;             for (int jj = 0; jj < 2; ++jj)
; #pragma unroll
;                 for (int kt = 0; kt < 2; ++kt) { f32x4 a = (MODE == 0) ? bb[jj][kt] + mneg[jj][kt] : bb[jj][kt];
;                     a = __builtin_amdgcn_mfma_f32_16x16x32_bf16(kf[jj][kt][0], qf[jj][0], a, 0, 0, 0);
;                     s[jj][kt] = __builtin_amdgcn_mfma_f32_16x16x32_bf16(kf[jj][kt][1], qf[jj][1], a, 0, 0, 0); }
;             u32x4 pw[2];
; #pragma unroll
;             for (int jj = 0; jj < 2; ++jj) {
;                 const float tm = vmax3(vmax3(s[jj][0][0], s[jj][0][1], s[jj][0][2]), vmax3(s[jj][0][3], s[jj][1][0], s[jj][1][1]), vmax3(s[jj][1][2], s[jj][1][3], s[jj][1][3]));
;                 const float mn = quad_max3(mrun[jj], tm);
;                 const float alpha = __builtin_amdgcn_exp2f(mrun[jj] - mn);
;                 mrun[jj] = mn;
;                 float rsum = 0.f;
; #pragma unroll
;                 for (int kt = 0; kt < 2; ++kt)
; #pragma unroll
;                     for (int e = 0; e < 4; ++e) { s[jj][kt][e] = __builtin_amdgcn_exp2f(s[jj][kt][e] - mn); rsum += s[jj][kt][e]; }
;                 lrun[jj] = lrun[jj] * alpha + rsum;
; #pragma unroll
;                 for (int dt = 0; dt < 4; ++dt) o[jj][dt] *= alpha;
;                 pw[jj].x = cvtpk(s[jj][0][0], s[jj][0][1]); pw[jj].y = cvtpk(s[jj][0][2], s[jj][0][3]); pw[jj].z = cvtpk(s[jj][1][0], s[jj][1][1]); pw[jj].w = cvtpk(s[jj][1][2], s[jj][1][3]);
;             }
; #pragma unroll
;             for (int jj = 0; jj < 2; ++jj)
; #pragma unroll
;                 for (int dt = 0; dt < 4; ++dt) {
;                     const bf16x8 vf = (bf16x8){vlo[jj][dt][0], vlo[jj][dt][1], vlo[jj][dt][2], vlo[jj][dt][3], vhi[jj][dt][0], vhi[jj][dt][1], vhi[jj][dt][2], vhi[jj][dt][3]};
;                     o[jj][dt] = __builtin_amdgcn_mfma_f32_16x16x32_bf16(vf, __builtin_bit_cast(bf16x8, pw[jj]), o[jj][dt], 0, 0, 0); }
;             __builtin_amdgcn_sched_barrier(0);
	v_pk_add_f32 v[160:161], v[112:113], v[160:161]
	v_pk_add_f32 v[158:159], v[110:111], v[158:159]
	s_nop 1
	v_mfma_f32_16x16x32_bf16 v[126:129], v[126:129], v[30:33], v[158:161]
	s_nop 2
	v_pk_add_f32 v[160:161], v[114:115], v[164:165]
	v_pk_add_f32 v[158:159], v[108:109], v[162:163]
	v_mfma_f32_16x16x32_bf16 v[126:129], v[134:137], v[26:29], v[126:129]
	v_pk_add_f32 v[136:137], v[106:107], v[168:169]
	v_pk_add_f32 v[134:135], v[102:103], v[166:167]
	v_mfma_f32_16x16x32_bf16 v[130:133], v[130:133], v[30:33], v[158:161]
	v_mfma_f32_16x16x32_bf16 v[130:133], v[138:141], v[26:29], v[130:133]
	s_nop 2
	v_maximum3_f32 v0, v126, v127, v128
	v_pk_add_f32 v[160:161], v[104:105], v[172:173]
	v_pk_add_f32 v[158:159], v[100:101], v[170:171]
	v_mfma_f32_16x16x32_bf16 v[134:137], v[142:145], v[22:25], v[134:137]
	v_mfma_f32_16x16x32_bf16 v[134:137], v[150:153], v[18:21], v[134:137]
	v_maximum3_f32 v138, v129, v130, v131
	v_maximum3_f32 v139, v132, v133, v133
	v_maximum3_f32 v0, v0, v138, v139
	v_mov_b32_e32 v138, v0
	s_nop 1
	v_permlane16_swap_b32_e32 v0, v138
	v_maximum3_f32 v0, v0, v138, v138
	v_mov_b32_e32 v138, v0
	s_nop 1
	v_permlane32_swap_b32_e32 v0, v138
	v_maximum3_f32 v162, v125, v0, v138
	v_mfma_f32_16x16x32_bf16 v[138:141], v[146:149], v[22:25], v[158:161]
	v_sub_f32_e32 v0, v125, v162
	v_sub_f32_e32 v125, v126, v162
	v_exp_f32_e32 v142, v125
	v_sub_f32_e32 v125, v127, v162
	v_exp_f32_e32 v144, v125
	v_sub_f32_e32 v125, v128, v162
	v_mfma_f32_16x16x32_bf16 v[138:141], v[154:157], v[18:21], v[138:141]
	v_exp_f32_e32 v146, v125
	v_sub_f32_e32 v125, v129, v162
	v_exp_f32_e32 v148, v125
	v_sub_f32_e32 v125, v130, v162
	v_exp_f32_e32 v130, v125
	v_sub_f32_e32 v125, v131, v162
	v_exp_f32_e32 v150, v125
	v_sub_f32_e32 v125, v132, v162
	v_exp_f32_e32 v132, v0
	v_sub_f32_e32 v0, v133, v162
	v_exp_f32_e32 v152, v125
	v_exp_f32_e32 v154, v0
	v_maximum3_f32 v0, v134, v135, v136
	v_maximum3_f32 v125, v137, v138, v139
	v_maximum3_f32 v129, v140, v141, v141
	v_maximum3_f32 v0, v0, v125, v129
	v_mov_b32_e32 v125, v0
	s_nop 1
	v_permlane16_swap_b32_e32 v0, v125
	v_maximum3_f32 v0, v0, v125, v125
	v_mov_b32_e32 v125, v0
	s_nop 1
	v_permlane32_swap_b32_e32 v0, v125
	v_maximum3_f32 v156, v124, v0, v125
	v_pk_mul_f32 v[56:57], v[56:57], v[132:133] op_sel_hi:[1,0]
	v_pk_mul_f32 v[54:55], v[54:55], v[132:133] op_sel_hi:[1,0]
	v_pk_mul_f32 v[64:65], v[64:65], v[132:133] op_sel_hi:[1,0]
	v_pk_mul_f32 v[62:63], v[62:63], v[132:133] op_sel_hi:[1,0]
	v_pk_mul_f32 v[60:61], v[60:61], v[132:133] op_sel_hi:[1,0]
	v_pk_mul_f32 v[58:59], v[58:59], v[132:133] op_sel_hi:[1,0]
	v_pk_mul_f32 v[52:53], v[52:53], v[132:133] op_sel_hi:[1,0]
	v_pk_mul_f32 v[50:51], v[50:51], v[132:133] op_sel_hi:[1,0]
	v_sub_f32_e32 v0, v134, v156
	v_sub_f32_e32 v133, v139, v156
	v_exp_f32_e32 v143, v0
	v_sub_f32_e32 v0, v135, v156
	v_sub_f32_e32 v131, v136, v156
	v_exp_f32_e32 v151, v133
	v_sub_f32_e32 v133, v140, v156
	v_exp_f32_e32 v145, v0
	v_sub_f32_e32 v0, v124, v156
	v_exp_f32_e32 v147, v131
	v_sub_f32_e32 v131, v137, v156
	v_exp_f32_e32 v153, v133
	v_sub_f32_e32 v133, v141, v156
	v_exp_f32_e32 v149, v131
	v_sub_f32_e32 v131, v138, v156
	v_exp_f32_e32 v155, v133
	v_exp_f32_e32 v133, v0
	v_exp_f32_e32 v131, v131
	v_cvt_pk_bf16_f32 v126, v142, v144
	v_cvt_pk_bf16_f32 v127, v146, v148
	v_cvt_pk_bf16_f32 v128, v130, v150
	v_cvt_pk_bf16_f32 v129, v152, v154
	v_pk_add_f32 v[124:125], v[142:143], 0 op_sel_hi:[1,0]
	v_mov_b32_e32 v0, v133
	v_pk_add_f32 v[124:125], v[144:145], v[124:125]
	s_setprio 1
	s_waitcnt lgkmcnt(10)
	v_mfma_f32_16x16x32_bf16 v[58:61], v[70:73], v[126:129], v[58:61]
	v_pk_mul_f32 v[48:49], v[48:49], v[0:1] op_sel_hi:[1,0]
	v_pk_mul_f32 v[46:47], v[46:47], v[0:1] op_sel_hi:[1,0]
	v_cvt_pk_bf16_f32 v70, v143, v145
	v_cvt_pk_bf16_f32 v71, v147, v149
	v_cvt_pk_bf16_f32 v72, v131, v151
	v_cvt_pk_bf16_f32 v73, v153, v155
	v_mfma_f32_16x16x32_bf16 v[54:57], v[78:81], v[126:129], v[54:57]
	v_pk_add_f32 v[78:79], v[146:147], v[124:125]
	v_pk_add_f32 v[78:79], v[148:149], v[78:79]
	s_waitcnt lgkmcnt(6)
	v_mfma_f32_16x16x32_bf16 v[46:49], v[14:17], v[70:73], v[46:49]
	v_pk_mul_f32 v[16:17], v[44:45], v[0:1] op_sel_hi:[1,0]
	v_pk_mul_f32 v[14:15], v[42:43], v[0:1] op_sel_hi:[1,0]
	v_mfma_f32_16x16x32_bf16 v[62:65], v[74:77], v[126:129], v[62:65]
	v_pk_add_f32 v[74:75], v[130:131], v[78:79]
	v_pk_add_f32 v[74:75], v[150:151], v[74:75]
	s_waitcnt lgkmcnt(4)
	v_mfma_f32_16x16x32_bf16 v[42:45], v[10:13], v[70:73], v[14:17]
	v_pk_mul_f32 v[12:13], v[40:41], v[0:1] op_sel_hi:[1,0]
	v_pk_mul_f32 v[10:11], v[38:39], v[0:1] op_sel_hi:[1,0]
	v_mfma_f32_16x16x32_bf16 v[50:53], v[66:69], v[126:129], v[50:53]
	v_pk_add_f32 v[66:67], v[152:153], v[74:75]
	v_pk_add_f32 v[14:15], v[154:155], v[66:67]
	s_waitcnt lgkmcnt(2)
	v_mfma_f32_16x16x32_bf16 v[38:41], v[6:9], v[70:73], v[10:13]
	v_pk_mul_f32 v[8:9], v[36:37], v[0:1] op_sel_hi:[1,0]
	v_pk_mul_f32 v[6:7], v[34:35], v[0:1] op_sel_hi:[1,0]
	v_pk_fma_f32 v[98:99], v[98:99], v[132:133], v[14:15]
	s_waitcnt lgkmcnt(0)
	v_mfma_f32_16x16x32_bf16 v[34:37], v[2:5], v[70:73], v[6:9]
	s_setprio 0
	v_mov_b32_e32 v125, v162
	v_mov_b32_e32 v124, v156
	s_cmp_eq_u32 s41, 2
	s_cbranch_scc1 .LBB0_281

; #define LAS __attribute__((address_space(3)))
; template <int MODE> ...
;     ...
;         if (t >= act0 && t < act0 + actn) {
;         const LAS unsigned char* Sl = ring + ((t + base) % 3) * SLOT;
; #pragma unroll
;         for (int hf = 0; hf < NH; ++hf) {
;             if (MODE == 1) { const int ks = ktok0 + 64 * t + 32 * hf;
;                 if (ks + 31 < qtok0 - 128 || ks > qtok0 + 31 + 128) continue; }
;             bf16x8 kf[2][2][2];
; #pragma unroll
;             for (int jj = 0; jj < 2; ++jj)
; #pragma unroll
;                 for (int kt = 0; kt < 2; ++kt)
; #pragma unroll
;                     for (int ks = 0; ks < 2; ++ks) kf[jj][kt][ks] = *(const LAS bf16x8*)(Sl + kad[jj][ks] + (32 * hf + 16 * kt) * 128);
;             f32x4 bb[2][2];
; #pragma unroll
;             for (int jj = 0; jj < 2; ++jj) { const LAS f32x4* bl = bcp + ((MODE == 0) ? (dr0 + t - act0) * 8 : 16 * t + 8 * hf) + bofs[jj];
; #pragma unroll
;                 for (int kt = 0; kt < 2; ++kt) bb[jj][kt] = bl[4 * kt]; }
;             s16x4 vlo[2][4], vhi[2][4];
; #pragma unroll
;             for (int jj = 0; jj < 2; ++jj)
; #pragma unroll
;                 for (int dt = 0; dt < 4; ++dt) { const LAS unsigned char* vp = Sl + vad[jj] + (32 * hf) * 128 + ((dt ^ sv) << 5);
;                     vlo[jj][dt] = __builtin_bit_cast(s16x4, __builtin_amdgcn_ds_read_tr16_b64_v4i16((LAS s16x4*)(vp)));
;                     vhi[jj][dt] = __builtin_bit_cast(s16x4, __builtin_amdgcn_ds_read_tr16_b64_v4i16((LAS s16x4*)(vp + 2048))); }
;             __builtin_amdgcn_sched_barrier(0);
.LBB0_305:
	s_add_i32 s0, s65, 2
	s_cmp_ge_i32 s0, s23
	s_cselect_b64 s[60:61], -1, 0
	s_cmp_lt_i32 s0, s45
	s_cselect_b64 s[66:67], -1, 0
	s_and_b64 s[60:61], s[60:61], s[66:67]
	s_andn2_b64 vcc, exec, s[60:61]
	s_cbranch_vccnz .LBB0_300
	s_add_i32 s0, s86, s65
	s_add_i32 s0, s0, 2
	s_mul_hi_i32 s14, s0, 0x55555556
	s_lshr_b32 s15, s14, 31
	s_add_i32 s14, s14, s15
	s_mul_i32 s14, s14, 3
	s_sub_i32 s0, s0, s14
	s_lshl_b32 s0, s0, 14
	s_add_i32 s0, s0, 0
	v_add_u32_e32 v2, s0, v89
	v_add_u32_e32 v3, s0, v88
	ds_read_b128 v[130:133], v2
	ds_read_b128 v[134:137], v2 offset:2048
	ds_read_b128 v[138:141], v3
	ds_read_b128 v[142:145], v3 offset:2048
	v_add_u32_e32 v2, s0, v92
	v_add_u32_e32 v3, s0, v91
	ds_read_b128 v[146:149], v2
	ds_read_b128 v[150:153], v2 offset:2048
	ds_read_b128 v[154:157], v3
	ds_read_b128 v[158:161], v3 offset:2048
	v_add_u32_e32 v2, s50, v128
	v_add_u32_e32 v3, s50, v127
	ds_read_b128 v[162:165], v2
	ds_read_b128 v[166:169], v2 offset:64
	ds_read_b128 v[170:173], v3
	ds_read_b128 v[174:177], v3 offset:64
	v_add_u32_e32 v3, s0, v178
	v_add_u32_e32 v4, s0, v179
	ds_read_b64_tr_b16 v[78:79], v3 offset:8192
	ds_read_b64_tr_b16 v[80:81], v3 offset:10240
	ds_read_b64_tr_b16 v[74:75], v4 offset:8192
	ds_read_b64_tr_b16 v[76:77], v4 offset:10240
	v_add_u32_e32 v3, s0, v180
	v_add_u32_e32 v2, s0, v181
	ds_read_b64_tr_b16 v[70:71], v3 offset:8192
	ds_read_b64_tr_b16 v[72:73], v3 offset:10240
	ds_read_b64_tr_b16 v[66:67], v2 offset:8192
	ds_read_b64_tr_b16 v[68:69], v2 offset:10240
	v_add_u32_e32 v3, s0, v182
	v_add_u32_e32 v4, s0, v183
	ds_read_b64_tr_b16 v[14:15], v3 offset:8192
	ds_read_b64_tr_b16 v[16:17], v3 offset:10240
	ds_read_b64_tr_b16 v[10:11], v4 offset:8192
	ds_read_b64_tr_b16 v[12:13], v4 offset:10240
	v_add_u32_e32 v3, s0, v184
	v_add_u32_e32 v4, s0, v185
	ds_read_b64_tr_b16 v[6:7], v3 offset:8192
	ds_read_b64_tr_b16 v[8:9], v3 offset:10240
	ds_read_b64_tr_b16 v[2:3], v4 offset:8192
	ds_read_b64_tr_b16 v[4:5], v4 offset:10240
	s_waitcnt lgkmcnt(14)
; __device__ __forceinline__ unsigned cvtpk(float lo, float hi) { f32x2 v = {lo, hi}; bf16x2_t b = __builtin_convertvector(v, bf16x2_t); return __builtin_bit_cast(unsigned, b); }
; __device__ __forceinline__ float vmax3(float a, float b, float c) { return __builtin_elementwise_maximum(__builtin_elementwise_maximum(a, b), c); }
; template <int MODE> ...
;     ...
;             f32x4 s[2][2];
; #pragma unroll
;             for (int jj = 0; jj < 2; ++jj)
; #pragma unroll
;                 for (int kt = 0; kt < 2; ++kt) { f32x4 a = (MODE == 0) ? bb[jj][kt] + mneg[jj][kt] : bb[jj][kt];
;                     a = __builtin_amdgcn_mfma_f32_16x16x32_bf16(kf[jj][kt][0], qf[jj][0], a, 0, 0, 0);
;                     s[jj][kt] = __builtin_amdgcn_mfma_f32_16x16x32_bf16(kf[jj][kt][1], qf[jj][1], a, 0, 0, 0); }
;             u32x4 pw[2];
; #pragma unroll
;             for (int jj = 0; jj < 2; ++jj) {
;                 const float tm = vmax3(vmax3(s[jj][0][0], s[jj][0][1], s[jj][0][2]), vmax3(s[jj][0][3], s[jj][1][0], s[jj][1][1]), vmax3(s[jj][1][2], s[jj][1][3], s[jj][1][3]));
;                 const float mn = quad_max3(mrun[jj], tm);
;                 const float alpha = __builtin_amdgcn_exp2f(mrun[jj] - mn);
;                 mrun[jj] = mn;
;                 float rsum = 0.f;
; #pragma unroll
;                 for (int kt = 0; kt < 2; ++kt)
; #pragma unroll
;                     for (int e = 0; e < 4; ++e) { s[jj][kt][e] = __builtin_amdgcn_exp2f(s[jj][kt][e] - mn); rsum += s[jj][kt][e]; }
;                 lrun[jj] = lrun[jj] * alpha + rsum;
; #pragma unroll
;                 for (int dt = 0; dt < 4; ++dt) o[jj][dt] *= alpha;
;                 pw[jj].x = cvtpk(s[jj][0][0], s[jj][0][1]); pw[jj].y = cvtpk(s[jj][0][2], s[jj][0][3]); pw[jj].z = cvtpk(s[jj][1][0], s[jj][1][1]); pw[jj].w = cvtpk(s[jj][1][2], s[jj][1][3]);
;             }
; #pragma unroll
;             for (int jj = 0; jj < 2; ++jj)
; #pragma unroll
;                 for (int dt = 0; dt < 4; ++dt) {
;                     const bf16x8 vf = (bf16x8){vlo[jj][dt][0], vlo[jj][dt][1], vlo[jj][dt][2], vlo[jj][dt][3], vhi[jj][dt][0], vhi[jj][dt][1], vhi[jj][dt][2], vhi[jj][dt][3]};
;                     o[jj][dt] = __builtin_amdgcn_mfma_f32_16x16x32_bf16(vf, __builtin_bit_cast(bf16x8, pw[jj]), o[jj][dt], 0, 0, 0); }
;             __builtin_amdgcn_sched_barrier(0);
	v_pk_add_f32 v[164:165], v[112:113], v[164:165]
	v_pk_add_f32 v[162:163], v[110:111], v[162:163]
	s_nop 1
	v_mfma_f32_16x16x32_bf16 v[130:133], v[130:133], v[30:33], v[162:165]
	s_nop 2
	v_pk_add_f32 v[164:165], v[114:115], v[168:169]
	v_pk_add_f32 v[162:163], v[108:109], v[166:167]
	v_mfma_f32_16x16x32_bf16 v[130:133], v[138:141], v[26:29], v[130:133]
	v_pk_add_f32 v[140:141], v[106:107], v[172:173]
	v_pk_add_f32 v[138:139], v[102:103], v[170:171]
	v_mfma_f32_16x16x32_bf16 v[134:137], v[134:137], v[30:33], v[162:165]
	v_mfma_f32_16x16x32_bf16 v[134:137], v[142:145], v[26:29], v[134:137]
	s_nop 2
	v_maximum3_f32 v129, v130, v131, v132
	v_pk_add_f32 v[164:165], v[104:105], v[176:177]
	v_pk_add_f32 v[162:163], v[100:101], v[174:175]
	v_mfma_f32_16x16x32_bf16 v[138:141], v[146:149], v[22:25], v[138:141]
	v_mfma_f32_16x16x32_bf16 v[138:141], v[154:157], v[18:21], v[138:141]
	v_maximum3_f32 v142, v133, v134, v135
	v_maximum3_f32 v143, v136, v137, v137
	v_maximum3_f32 v129, v129, v142, v143
	v_mov_b32_e32 v142, v129
	s_nop 1
	v_permlane16_swap_b32_e32 v129, v142
	v_maximum3_f32 v129, v129, v142, v142
	v_mov_b32_e32 v142, v129
	s_nop 1
	v_permlane32_swap_b32_e32 v129, v142
	v_maximum3_f32 v129, v125, v129, v142
	v_mfma_f32_16x16x32_bf16 v[142:145], v[150:153], v[22:25], v[162:165]
	v_pk_add_f32 v[130:131], v[130:131], v[128:129] op_sel:[0,1] op_sel_hi:[1,1] neg_lo:[0,1] neg_hi:[0,1]
	v_pk_add_f32 v[132:133], v[132:133], v[128:129] op_sel:[0,1] op_sel_hi:[1,1] neg_lo:[0,1] neg_hi:[0,1]
	v_pk_add_f32 v[134:135], v[134:135], v[128:129] op_sel:[0,1] op_sel_hi:[1,1] neg_lo:[0,1] neg_hi:[0,1]
	v_pk_add_f32 v[136:137], v[136:137], v[128:129] op_sel:[0,1] op_sel_hi:[1,1] neg_lo:[0,1] neg_hi:[0,1]
	v_sub_f32_e32 v125, v125, v129
	v_mfma_f32_16x16x32_bf16 v[142:145], v[158:161], v[18:21], v[142:145]
	v_exp_f32_e32 v146, v130
	v_exp_f32_e32 v148, v131
	v_exp_f32_e32 v150, v132
	v_exp_f32_e32 v152, v133
	v_exp_f32_e32 v154, v135
	v_exp_f32_e32 v156, v136
	v_exp_f32_e32 v158, v137
	v_exp_f32_e32 v134, v134
	v_exp_f32_e32 v136, v125
	v_maximum3_f32 v125, v138, v139, v140
	v_maximum3_f32 v133, v141, v142, v143
	v_maximum3_f32 v135, v144, v145, v145
	v_maximum3_f32 v125, v125, v133, v135
	v_mov_b32_e32 v133, v125
	s_nop 1
	v_permlane16_swap_b32_e32 v125, v133
	v_maximum3_f32 v125, v125, v133, v133
	v_mov_b32_e32 v133, v125
	s_nop 1
	v_permlane32_swap_b32_e32 v125, v133
	v_maximum3_f32 v160, v124, v125, v133
	v_pk_add_f32 v[138:139], v[138:139], v[160:161] op_sel_hi:[1,0] neg_lo:[0,1] neg_hi:[0,1]
	v_pk_add_f32 v[140:141], v[140:141], v[160:161] op_sel_hi:[1,0] neg_lo:[0,1] neg_hi:[0,1]
	v_pk_add_f32 v[142:143], v[142:143], v[160:161] op_sel_hi:[1,0] neg_lo:[0,1] neg_hi:[0,1]
	v_pk_add_f32 v[144:145], v[144:145], v[160:161] op_sel_hi:[1,0] neg_lo:[0,1] neg_hi:[0,1]
	v_sub_f32_e32 v137, v124, v160
	v_exp_f32_e32 v147, v138
	v_pk_mul_f32 v[56:57], v[56:57], v[136:137] op_sel_hi:[1,0]
	v_exp_f32_e32 v149, v139
	v_pk_mul_f32 v[54:55], v[54:55], v[136:137] op_sel_hi:[1,0]
	v_exp_f32_e32 v151, v140
	v_pk_mul_f32 v[64:65], v[64:65], v[136:137] op_sel_hi:[1,0]
	v_exp_f32_e32 v153, v141
	v_pk_mul_f32 v[62:63], v[62:63], v[136:137] op_sel_hi:[1,0]
	v_exp_f32_e32 v155, v143
	v_pk_mul_f32 v[60:61], v[60:61], v[136:137] op_sel_hi:[1,0]
	v_exp_f32_e32 v157, v144
	v_pk_mul_f32 v[58:59], v[58:59], v[136:137] op_sel_hi:[1,0]
	v_exp_f32_e32 v159, v145
	v_pk_mul_f32 v[52:53], v[52:53], v[136:137] op_sel_hi:[1,0]
	v_exp_f32_e32 v135, v142
	v_pk_mul_f32 v[50:51], v[50:51], v[136:137] op_sel_hi:[1,0]
	v_exp_f32_e32 v137, v137
	v_cvt_pk_bf16_f32 v130, v146, v148
	v_cvt_pk_bf16_f32 v131, v150, v152
	v_cvt_pk_bf16_f32 v132, v134, v154
	v_cvt_pk_bf16_f32 v133, v156, v158
	s_setprio 1
	s_waitcnt lgkmcnt(12)
	v_mfma_f32_16x16x32_bf16 v[62:65], v[74:77], v[130:133], v[62:65]
	v_pk_add_f32 v[124:125], v[146:147], v[148:149]
	v_pk_mul_f32 v[48:49], v[48:49], v[136:137] op_sel:[0,1] op_sel_hi:[1,1]
	s_waitcnt lgkmcnt(10)
	v_mfma_f32_16x16x32_bf16 v[58:61], v[70:73], v[130:133], v[58:61]
	v_pk_mul_f32 v[46:47], v[46:47], v[136:137] op_sel:[0,1] op_sel_hi:[1,1]
	v_cvt_pk_bf16_f32 v70, v147, v149
	v_cvt_pk_bf16_f32 v71, v151, v153
	v_cvt_pk_bf16_f32 v72, v135, v155
	v_cvt_pk_bf16_f32 v73, v157, v159
	v_mfma_f32_16x16x32_bf16 v[54:57], v[78:81], v[130:133], v[54:57]
	v_pk_add_f32 v[78:79], v[150:151], v[124:125]
	v_pk_add_f32 v[78:79], v[152:153], v[78:79]
	s_waitcnt lgkmcnt(6)
	v_mfma_f32_16x16x32_bf16 v[46:49], v[14:17], v[70:73], v[46:49]
	v_pk_mul_f32 v[16:17], v[44:45], v[136:137] op_sel:[0,1] op_sel_hi:[1,1]
	v_pk_mul_f32 v[14:15], v[42:43], v[136:137] op_sel:[0,1] op_sel_hi:[1,1]
	v_pk_add_f32 v[74:75], v[134:135], v[78:79]
	v_mfma_f32_16x16x32_bf16 v[50:53], v[66:69], v[130:133], v[50:53]
	v_pk_add_f32 v[74:75], v[154:155], v[74:75]
	v_pk_add_f32 v[66:67], v[156:157], v[74:75]
	s_waitcnt lgkmcnt(4)
	v_mfma_f32_16x16x32_bf16 v[42:45], v[10:13], v[70:73], v[14:17]
	v_pk_mul_f32 v[12:13], v[40:41], v[136:137] op_sel:[0,1] op_sel_hi:[1,1]
	v_pk_mul_f32 v[10:11], v[38:39], v[136:137] op_sel:[0,1] op_sel_hi:[1,1]
	v_pk_add_f32 v[14:15], v[158:159], v[66:67]
	s_waitcnt lgkmcnt(2)
	v_mfma_f32_16x16x32_bf16 v[38:41], v[6:9], v[70:73], v[10:13]
	v_pk_mul_f32 v[8:9], v[36:37], v[136:137] op_sel:[0,1] op_sel_hi:[1,1]
	v_pk_mul_f32 v[6:7], v[34:35], v[136:137] op_sel:[0,1] op_sel_hi:[1,1]
	v_pk_fma_f32 v[98:99], v[98:99], v[136:137], v[14:15]
	s_waitcnt lgkmcnt(0)
	v_mfma_f32_16x16x32_bf16 v[34:37], v[2:5], v[70:73], v[6:9]
	s_setprio 0
	v_mov_b32_e32 v125, v129
	v_mov_b32_e32 v124, v160
	s_branch .LBB0_300

; template <int MODE> ...
;     ...
;         const LAS unsigned char* Sl = ring + ((t + base) % 3) * SLOT;
; #pragma unroll
;         for (int hf = 0; hf < NH; ++hf) {
;             if (MODE == 1) { const int ks = ktok0 + 64 * t + 32 * hf;
;                 if (ks + 31 < qtok0 - 128 || ks > qtok0 + 31 + 128) continue; }
;             bf16x8 kf[2][2][2];
; #pragma unroll
;             for (int jj = 0; jj < 2; ++jj)
; #pragma unroll
;                 for (int kt = 0; kt < 2; ++kt)
; #pragma unroll
;                     for (int ks = 0; ks < 2; ++ks) kf[jj][kt][ks] = *(const LAS bf16x8*)(Sl + kad[jj][ks] + (32 * hf + 16 * kt) * 128);
;             f32x4 bb[2][2];
; #pragma unroll
;             for (int jj = 0; jj < 2; ++jj) { const LAS f32x4* bl = bcp + ((MODE == 0) ? (dr0 + t - act0) * 8 : 16 * t + 8 * hf) + bofs[jj];
; #pragma unroll
;                 for (int kt = 0; kt < 2; ++kt) bb[jj][kt] = bl[4 * kt]; }
;             s16x4 vlo[2][4], vhi[2][4];
; #pragma unroll
;             for (int jj = 0; jj < 2; ++jj)
; #pragma unroll
;                 for (int dt = 0; dt < 4; ++dt) { const LAS unsigned char* vp = Sl + vad[jj] + (32 * hf) * 128 + ((dt ^ sv) << 5);
;                     vlo[jj][dt] = __builtin_bit_cast(s16x4, __builtin_amdgcn_ds_read_tr16_b64_v4i16((LAS s16x4*)(vp)));
;                     vhi[jj][dt] = __builtin_bit_cast(s16x4, __builtin_amdgcn_ds_read_tr16_b64_v4i16((LAS s16x4*)(vp + 2048))); }
;             __builtin_amdgcn_sched_barrier(0);
;             f32x4 s[2][2];
; #pragma unroll
;             for (int jj = 0; jj < 2; ++jj)
; #pragma unroll
;                 for (int kt = 0; kt < 2; ++kt) { f32x4 a = (MODE == 0) ? bb[jj][kt] + mneg[jj][kt] : bb[jj][kt];
;                     a = __builtin_amdgcn_mfma_f32_16x16x32_bf16(kf[jj][kt][0], qf[jj][0], a, 0, 0, 0);
;                     s[jj][kt] = __builtin_amdgcn_mfma_f32_16x16x32_bf16(kf[jj][kt][1], qf[jj][1], a, 0, 0, 0); }
;             u32x4 pw[2];
; #pragma unroll
;             for (int jj = 0; jj < 2; ++jj) {
;                 const float tm = vmax3(vmax3(s[jj][0][0], s[jj][0][1], s[jj][0][2]), vmax3(s[jj][0][3], s[jj][1][0], s[jj][1][1]), vmax3(s[jj][1][2], s[jj][1][3], s[jj][1][3]));
;                 const float mn = quad_max3(mrun[jj], tm);
;                 const float alpha = __builtin_amdgcn_exp2f(mrun[jj] - mn);
;                 mrun[jj] = mn;
;                 float rsum = 0.f;
.LBB0_343:
	s_add_i32 s0, s86, s65
	s_mul_hi_i32 s14, s0, 0x55555556
	s_lshr_b32 s15, s14, 31
	s_add_i32 s14, s14, s15
	s_mul_i32 s14, s14, 3
	s_sub_i32 s0, s0, s14
	s_lshl_b32 s0, s0, 14
	s_add_i32 s0, s0, 0
	s_add_i32 s14, s27, 31
	s_cmp_lt_i32 s14, s41
	s_cselect_b64 s[50:51], -1, 0
	s_cmp_gt_i32 s27, s45
	s_cselect_b64 s[52:53], -1, 0
	s_or_b64 s[50:51], s[50:51], s[52:53]
	v_add_u32_e32 v0, s0, v78
	s_and_b64 vcc, exec, s[50:51]
	v_add_u32_e32 v98, s0, v70
	v_add_u32_e32 v97, s0, v71
	v_add_u32_e32 v96, s40, v80
	v_add_u32_e32 v85, s40, v79
	v_add_u32_e32 v84, v0, v74
	v_add_u32_e32 v83, v0, v75
	v_add_u32_e32 v81, v0, v76
	v_add_u32_e32 v0, v0, v77
	s_cbranch_vccnz .LBB0_345
	v_add_u32_e32 v2, 0x10000, v96
	v_add_u32_e32 v3, 0x10040, v96
	ds_read_b128 v[100:103], v98
	ds_read_b128 v[104:107], v98 offset:2048
	ds_read_b128 v[108:111], v97
	ds_read_b128 v[112:115], v97 offset:2048
	ds_read_b128 v[118:121], v2
	ds_read_b128 v[122:125], v3
	v_add_u32_e32 v2, 0x10000, v85
	v_add_u32_e32 v3, 0x10040, v85
	ds_read_b128 v[126:129], v2
	ds_read_b128 v[130:133], v3
	ds_read_b64_tr_b16 v[14:15], v84 offset:8192
	ds_read_b64_tr_b16 v[16:17], v84 offset:10240
	ds_read_b64_tr_b16 v[10:11], v83 offset:8192
	ds_read_b64_tr_b16 v[12:13], v83 offset:10240
	ds_read_b64_tr_b16 v[6:7], v81 offset:8192
	ds_read_b64_tr_b16 v[8:9], v81 offset:10240
	ds_read_b64_tr_b16 v[2:3], v0 offset:8192
	ds_read_b64_tr_b16 v[4:5], v0 offset:10240
	s_waitcnt lgkmcnt(11)
	v_mfma_f32_16x16x32_bf16 v[118:121], v[100:103], v[30:33], v[118:121]
	s_waitcnt lgkmcnt(10)
	v_mfma_f32_16x16x32_bf16 v[122:125], v[104:107], v[30:33], v[122:125]
	v_mfma_f32_16x16x32_bf16 v[118:121], v[108:111], v[26:29], v[118:121]
	v_mfma_f32_16x16x32_bf16 v[122:125], v[112:115], v[26:29], v[122:125]
	s_waitcnt lgkmcnt(9)
	v_mfma_f32_16x16x32_bf16 v[100:103], v[100:103], v[22:25], v[126:129]
	s_nop 4
	v_maximum3_f32 v99, v118, v119, v120
	v_mfma_f32_16x16x32_bf16 v[100:103], v[108:111], v[18:21], v[100:103]
	v_maximum3_f32 v108, v121, v122, v123
	v_maximum3_f32 v109, v124, v125, v125
	v_maximum3_f32 v99, v99, v108, v109
	s_waitcnt lgkmcnt(8)
	v_mfma_f32_16x16x32_bf16 v[104:107], v[104:107], v[22:25], v[130:133]
	v_mov_b32_e32 v108, v99
	s_nop 1
	v_permlane16_swap_b32_e32 v99, v108
	v_maximum3_f32 v99, v99, v108, v108
	v_mfma_f32_16x16x32_bf16 v[104:107], v[112:115], v[18:21], v[104:107]
	v_mov_b32_e32 v108, v99
	s_nop 1
	v_permlane32_swap_b32_e32 v99, v108
	v_maximum3_f32 v99, v82, v99, v108
	v_sub_f32_e32 v82, v82, v99
	v_exp_f32_e32 v130, v82
	v_maximum3_f32 v82, v100, v101, v102
	v_maximum3_f32 v113, v103, v104, v105
	v_maximum3_f32 v115, v106, v107, v107
	v_maximum3_f32 v82, v82, v113, v115
	v_mov_b32_e32 v113, v82
	s_nop 1
	v_permlane16_swap_b32_e32 v82, v113
	v_maximum3_f32 v82, v82, v113, v113
	v_mov_b32_e32 v113, v82
	s_nop 1
	v_permlane32_swap_b32_e32 v82, v113
	v_maximum3_f32 v117, v95, v82, v113
	v_sub_f32_e32 v108, v118, v99
	v_sub_f32_e32 v82, v95, v117
	v_sub_f32_e32 v95, v100, v117
	v_exp_f32_e32 v112, v108
	v_sub_f32_e32 v108, v119, v99
	v_exp_f32_e32 v113, v95
	v_sub_f32_e32 v95, v101, v117
	v_exp_f32_e32 v114, v108
	v_sub_f32_e32 v108, v120, v99
	v_exp_f32_e32 v115, v95
	v_sub_f32_e32 v95, v102, v117
	v_exp_f32_e32 v118, v108
	v_sub_f32_e32 v108, v121, v99
	v_exp_f32_e32 v119, v95
	v_sub_f32_e32 v95, v103, v117
	v_exp_f32_e32 v120, v108
	v_sub_f32_e32 v108, v122, v99
	v_exp_f32_e32 v121, v95
	v_sub_f32_e32 v95, v104, v117
	v_exp_f32_e32 v122, v108
	v_sub_f32_e32 v108, v123, v99
	v_exp_f32_e32 v123, v95
	v_sub_f32_e32 v95, v105, v117
	v_pk_add_f32 v[100:101], v[112:113], 0 op_sel_hi:[1,0]
	v_exp_f32_e32 v126, v108
	v_sub_f32_e32 v108, v124, v99
	v_exp_f32_e32 v127, v95
	v_sub_f32_e32 v95, v106, v117
	v_pk_add_f32 v[100:101], v[114:115], v[100:101]
	v_exp_f32_e32 v124, v108
	v_sub_f32_e32 v108, v125, v99
	v_exp_f32_e32 v125, v95
	v_sub_f32_e32 v95, v107, v117
	v_pk_add_f32 v[100:101], v[118:119], v[100:101]
	v_exp_f32_e32 v128, v108
	v_pk_mul_f32 v[52:53], v[52:53], v[130:131] op_sel_hi:[1,0]
	v_pk_mul_f32 v[50:51], v[50:51], v[130:131] op_sel_hi:[1,0]
	v_pk_mul_f32 v[56:57], v[56:57], v[130:131] op_sel_hi:[1,0]
	v_pk_mul_f32 v[54:55], v[54:55], v[130:131] op_sel_hi:[1,0]
	v_pk_mul_f32 v[60:61], v[60:61], v[130:131] op_sel_hi:[1,0]
	v_pk_mul_f32 v[58:59], v[58:59], v[130:131] op_sel_hi:[1,0]
	v_pk_mul_f32 v[64:65], v[64:65], v[130:131] op_sel_hi:[1,0]
	v_pk_mul_f32 v[62:63], v[62:63], v[130:131] op_sel_hi:[1,0]
	v_exp_f32_e32 v129, v95
	v_pk_add_f32 v[100:101], v[120:121], v[100:101]
	v_exp_f32_e32 v131, v82
	v_pk_add_f32 v[100:101], v[122:123], v[100:101]
	v_cvt_pk_bf16_f32 v108, v112, v114
	v_pk_add_f32 v[100:101], v[126:127], v[100:101]
	v_mov_b32_e32 v82, v131
	v_pk_add_f32 v[100:101], v[124:125], v[100:101]
	v_cvt_pk_bf16_f32 v109, v118, v120
	v_pk_add_f32 v[100:101], v[128:129], v[100:101]
	v_cvt_pk_bf16_f32 v110, v122, v126
	v_cvt_pk_bf16_f32 v111, v124, v128
	v_pk_fma_f32 v[88:89], v[88:89], v[130:131], v[100:101]
	v_pk_mul_f32 v[36:37], v[36:37], v[82:83] op_sel_hi:[1,0]
	v_pk_mul_f32 v[34:35], v[34:35], v[82:83] op_sel_hi:[1,0]
	v_pk_mul_f32 v[40:41], v[40:41], v[82:83] op_sel_hi:[1,0]
	v_pk_mul_f32 v[38:39], v[38:39], v[82:83] op_sel_hi:[1,0]
	v_pk_mul_f32 v[44:45], v[44:45], v[82:83] op_sel_hi:[1,0]
	v_pk_mul_f32 v[42:43], v[42:43], v[82:83] op_sel_hi:[1,0]
	v_pk_mul_f32 v[48:49], v[48:49], v[82:83] op_sel_hi:[1,0]
	v_pk_mul_f32 v[46:47], v[46:47], v[82:83] op_sel_hi:[1,0]
	v_cvt_pk_bf16_f32 v100, v113, v115
	v_cvt_pk_bf16_f32 v101, v119, v121
	v_cvt_pk_bf16_f32 v102, v123, v127
	v_cvt_pk_bf16_f32 v103, v125, v129
	s_setprio 1
	s_waitcnt lgkmcnt(6)
	v_mfma_f32_16x16x32_bf16 v[50:53], v[14:17], v[108:111], v[50:53]
	s_waitcnt lgkmcnt(4)
	v_mfma_f32_16x16x32_bf16 v[54:57], v[10:13], v[108:111], v[54:57]
	s_waitcnt lgkmcnt(2)
	v_mfma_f32_16x16x32_bf16 v[58:61], v[6:9], v[108:111], v[58:61]
	s_waitcnt lgkmcnt(0)
	v_mfma_f32_16x16x32_bf16 v[62:65], v[2:5], v[108:111], v[62:65]
	v_mfma_f32_16x16x32_bf16 v[34:37], v[14:17], v[100:103], v[34:37]
	v_mfma_f32_16x16x32_bf16 v[38:41], v[10:13], v[100:103], v[38:41]
	v_mfma_f32_16x16x32_bf16 v[42:45], v[6:9], v[100:103], v[42:45]
	v_mfma_f32_16x16x32_bf16 v[46:49], v[2:5], v[100:103], v[46:49]
	s_setprio 0
	v_mov_b32_e32 v82, v99
	v_mov_b32_e32 v95, v117
; template <int MODE> ...
;     ...
;         for (int hf = 0; hf < NH; ++hf) {
;             if (MODE == 1) { const int ks = ktok0 + 64 * t + 32 * hf;
;                 if (ks + 31 < qtok0 - 128 || ks > qtok0 + 31 + 128) continue; }
;             bf16x8 kf[2][2][2];
; #pragma unroll
;             for (int jj = 0; jj < 2; ++jj)
; #pragma unroll
;                 for (int kt = 0; kt < 2; ++kt)
; #pragma unroll
;                     for (int ks = 0; ks < 2; ++ks) kf[jj][kt][ks] = *(const LAS bf16x8*)(Sl + kad[jj][ks] + (32 * hf + 16 * kt) * 128);
;             f32x4 bb[2][2];
; #pragma unroll
;             for (int jj = 0; jj < 2; ++jj) { const LAS f32x4* bl = bcp + ((MODE == 0) ? (dr0 + t - act0) * 8 : 16 * t + 8 * hf) + bofs[jj];
; #pragma unroll
;                 for (int kt = 0; kt < 2; ++kt) bb[jj][kt] = bl[4 * kt]; }
;             s16x4 vlo[2][4], vhi[2][4];
; #pragma unroll
;             for (int jj = 0; jj < 2; ++jj)
; #pragma unroll
;                 for (int dt = 0; dt < 4; ++dt) { const LAS unsigned char* vp = Sl + vad[jj] + (32 * hf) * 128 + ((dt ^ sv) << 5);
;                     vlo[jj][dt] = __builtin_bit_cast(s16x4, __builtin_amdgcn_ds_read_tr16_b64_v4i16((LAS s16x4*)(vp)));
;                     vhi[jj][dt] = __builtin_bit_cast(s16x4, __builtin_amdgcn_ds_read_tr16_b64_v4i16((LAS s16x4*)(vp + 2048))); }
;             __builtin_amdgcn_sched_barrier(0);
;             f32x4 s[2][2];
; #pragma unroll
;             for (int jj = 0; jj < 2; ++jj)
; #pragma unroll
;                 for (int kt = 0; kt < 2; ++kt) { f32x4 a = (MODE == 0) ? bb[jj][kt] + mneg[jj][kt] : bb[jj][kt];
;                     a = __builtin_amdgcn_mfma_f32_16x16x32_bf16(kf[jj][kt][0], qf[jj][0], a, 0, 0, 0);
;                     s[jj][kt] = __builtin_amdgcn_mfma_f32_16x16x32_bf16(kf[jj][kt][1], qf[jj][1], a, 0, 0, 0); }
;             u32x4 pw[2];
; #pragma unroll
;             for (int jj = 0; jj < 2; ++jj) {
;                 const float tm = vmax3(vmax3(s[jj][0][0], s[jj][0][1], s[jj][0][2]), vmax3(s[jj][0][3], s[jj][1][0], s[jj][1][1]), vmax3(s[jj][1][2], s[jj][1][3], s[jj][1][3]));
;                 const float mn = quad_max3(mrun[jj], tm);
;                 const float alpha = __builtin_amdgcn_exp2f(mrun[jj] - mn);
;                 mrun[jj] = mn;
;                 float rsum = 0.f;
; #pragma unroll
;                 for (int kt = 0; kt < 2; ++kt)
; #pragma unroll
.LBB0_345:
	s_add_i32 s0, s27, 32
	s_add_i32 s14, s27, 63
	s_cmp_lt_i32 s14, s41
	s_cselect_b64 s[50:51], -1, 0
	s_cmp_gt_i32 s0, s45
	s_cselect_b64 s[52:53], -1, 0
	s_or_b64 s[50:51], s[50:51], s[52:53]
	s_and_b64 vcc, exec, s[50:51]
	s_cbranch_vccnz .LBB0_333
	v_add_u32_e32 v2, 0x10080, v96
	v_add_u32_e32 v3, 0x100c0, v96
	ds_read_b128 v[100:103], v98 offset:4096
	ds_read_b128 v[104:107], v98 offset:6144
	ds_read_b128 v[108:111], v97 offset:4096
	ds_read_b128 v[112:115], v97 offset:6144
	ds_read_b128 v[96:99], v2
	ds_read_b128 v[118:121], v3
	v_add_u32_e32 v2, 0x10080, v85
	v_add_u32_e32 v3, 0x100c0, v85
	ds_read_b128 v[122:125], v2
	ds_read_b128 v[126:129], v3
	ds_read_b64_tr_b16 v[14:15], v84 offset:12288
	ds_read_b64_tr_b16 v[16:17], v84 offset:14336
	ds_read_b64_tr_b16 v[10:11], v83 offset:12288
	ds_read_b64_tr_b16 v[12:13], v83 offset:14336
	ds_read_b64_tr_b16 v[6:7], v81 offset:12288
	ds_read_b64_tr_b16 v[8:9], v81 offset:14336
	ds_read_b64_tr_b16 v[2:3], v0 offset:12288
	ds_read_b64_tr_b16 v[4:5], v0 offset:14336
	s_waitcnt lgkmcnt(11)
	v_mfma_f32_16x16x32_bf16 v[96:99], v[100:103], v[30:33], v[96:99]
	s_waitcnt lgkmcnt(10)
	v_mfma_f32_16x16x32_bf16 v[118:121], v[104:107], v[30:33], v[118:121]
	v_mfma_f32_16x16x32_bf16 v[96:99], v[108:111], v[26:29], v[96:99]
	v_mfma_f32_16x16x32_bf16 v[118:121], v[112:115], v[26:29], v[118:121]
	s_waitcnt lgkmcnt(9)
	v_mfma_f32_16x16x32_bf16 v[100:103], v[100:103], v[22:25], v[122:125]
	s_nop 4
	v_maximum3_f32 v0, v96, v97, v98
	v_maximum3_f32 v81, v99, v118, v119
	v_maximum3_f32 v83, v120, v121, v121
	v_maximum3_f32 v0, v0, v81, v83
	v_mov_b32_e32 v81, v0
	s_waitcnt lgkmcnt(8)
	v_mfma_f32_16x16x32_bf16 v[104:107], v[104:107], v[22:25], v[126:129]
	v_permlane16_swap_b32_e32 v0, v81
	v_maximum3_f32 v0, v0, v81, v81
	v_mov_b32_e32 v81, v0
	s_nop 1
	v_permlane32_swap_b32_e32 v0, v81
	v_mfma_f32_16x16x32_bf16 v[100:103], v[108:111], v[18:21], v[100:103]
	v_maximum3_f32 v81, v82, v0, v81
	v_sub_f32_e32 v0, v82, v81
	v_sub_f32_e32 v82, v96, v81
	v_mfma_f32_16x16x32_bf16 v[104:107], v[112:115], v[18:21], v[104:107]
	v_exp_f32_e32 v96, v82
	v_sub_f32_e32 v82, v97, v81
	v_exp_f32_e32 v108, v82
	v_sub_f32_e32 v82, v98, v81
	v_exp_f32_e32 v98, v82
	v_sub_f32_e32 v82, v99, v81
	v_exp_f32_e32 v122, v0
	v_maximum3_f32 v0, v100, v101, v102
	v_maximum3_f32 v97, v103, v104, v105
	v_maximum3_f32 v99, v106, v107, v107
	v_maximum3_f32 v0, v0, v97, v99
	v_mov_b32_e32 v97, v0
	s_nop 1
	v_permlane16_swap_b32_e32 v0, v97
	v_maximum3_f32 v0, v0, v97, v97
	v_mov_b32_e32 v97, v0
	s_nop 1
	v_permlane32_swap_b32_e32 v0, v97
	v_maximum3_f32 v117, v95, v0, v97
	v_sub_f32_e32 v0, v95, v117
	v_sub_f32_e32 v95, v100, v117
	v_exp_f32_e32 v97, v95
	v_sub_f32_e32 v95, v101, v117
	v_exp_f32_e32 v109, v95
	v_sub_f32_e32 v95, v102, v117
	v_exp_f32_e32 v99, v95
	v_sub_f32_e32 v95, v103, v117
	v_exp_f32_e32 v110, v82
	v_sub_f32_e32 v82, v118, v81
	v_exp_f32_e32 v111, v95
	v_sub_f32_e32 v95, v104, v117
	v_exp_f32_e32 v112, v82
	v_sub_f32_e32 v82, v119, v81
	v_exp_f32_e32 v113, v95
	v_sub_f32_e32 v95, v105, v117
	v_exp_f32_e32 v114, v82
	v_sub_f32_e32 v82, v120, v81
	v_exp_f32_e32 v115, v95
	v_sub_f32_e32 v95, v106, v117
	v_exp_f32_e32 v118, v82
	v_sub_f32_e32 v82, v121, v81
	v_pk_mul_f32 v[52:53], v[52:53], v[122:123] op_sel_hi:[1,0]
	v_pk_mul_f32 v[50:51], v[50:51], v[122:123] op_sel_hi:[1,0]
	v_pk_mul_f32 v[56:57], v[56:57], v[122:123] op_sel_hi:[1,0]
	v_pk_mul_f32 v[54:55], v[54:55], v[122:123] op_sel_hi:[1,0]
	v_pk_mul_f32 v[60:61], v[60:61], v[122:123] op_sel_hi:[1,0]
	v_pk_mul_f32 v[58:59], v[58:59], v[122:123] op_sel_hi:[1,0]
	v_pk_mul_f32 v[64:65], v[64:65], v[122:123] op_sel_hi:[1,0]
	v_pk_mul_f32 v[62:63], v[62:63], v[122:123] op_sel_hi:[1,0]
	v_exp_f32_e32 v119, v95
	v_sub_f32_e32 v95, v107, v117
	v_exp_f32_e32 v123, v0
	v_exp_f32_e32 v120, v82
	v_pk_add_f32 v[100:101], v[96:97], 0 op_sel_hi:[1,0]
	v_exp_f32_e32 v121, v95
	v_pk_add_f32 v[100:101], v[108:109], v[100:101]
	v_mov_b32_e32 v0, v123
	v_pk_add_f32 v[100:101], v[98:99], v[100:101]
	v_cvt_pk_bf16_f32 v82, v96, v108
	v_pk_add_f32 v[100:101], v[110:111], v[100:101]
	v_cvt_pk_bf16_f32 v83, v98, v110
	v_cvt_pk_bf16_f32 v84, v112, v114
	v_cvt_pk_bf16_f32 v85, v118, v120
	v_pk_add_f32 v[100:101], v[112:113], v[100:101]
	v_pk_mul_f32 v[36:37], v[36:37], v[0:1] op_sel_hi:[1,0]
	v_pk_mul_f32 v[34:35], v[34:35], v[0:1] op_sel_hi:[1,0]
	v_pk_mul_f32 v[40:41], v[40:41], v[0:1] op_sel_hi:[1,0]
	v_pk_mul_f32 v[38:39], v[38:39], v[0:1] op_sel_hi:[1,0]
	v_pk_mul_f32 v[44:45], v[44:45], v[0:1] op_sel_hi:[1,0]
	v_pk_mul_f32 v[42:43], v[42:43], v[0:1] op_sel_hi:[1,0]
	v_pk_mul_f32 v[48:49], v[48:49], v[0:1] op_sel_hi:[1,0]
	v_pk_mul_f32 v[46:47], v[46:47], v[0:1] op_sel_hi:[1,0]
	v_cvt_pk_bf16_f32 v96, v97, v109
	v_cvt_pk_bf16_f32 v97, v99, v111
	v_cvt_pk_bf16_f32 v98, v113, v115
	v_cvt_pk_bf16_f32 v99, v119, v121
	v_pk_add_f32 v[100:101], v[114:115], v[100:101]
	s_setprio 1
	s_waitcnt lgkmcnt(6)
	v_mfma_f32_16x16x32_bf16 v[50:53], v[14:17], v[82:85], v[50:53]
	v_pk_add_f32 v[100:101], v[118:119], v[100:101]
	v_pk_add_f32 v[100:101], v[120:121], v[100:101]
	s_waitcnt lgkmcnt(4)
	v_mfma_f32_16x16x32_bf16 v[54:57], v[10:13], v[82:85], v[54:57]
	v_fma_f32 v88, v88, v122, v100
	v_fma_f32 v89, v89, v123, v101
	s_waitcnt lgkmcnt(2)
	v_mfma_f32_16x16x32_bf16 v[58:61], v[6:9], v[82:85], v[58:61]
	s_waitcnt lgkmcnt(0)
	v_mfma_f32_16x16x32_bf16 v[62:65], v[2:5], v[82:85], v[62:65]
	v_mfma_f32_16x16x32_bf16 v[34:37], v[14:17], v[96:99], v[34:37]
	v_mfma_f32_16x16x32_bf16 v[38:41], v[10:13], v[96:99], v[38:41]
	v_mfma_f32_16x16x32_bf16 v[42:45], v[6:9], v[96:99], v[42:45]
	v_mfma_f32_16x16x32_bf16 v[46:49], v[2:5], v[96:99], v[46:49]
	s_setprio 0
	v_mov_b32_e32 v95, v117
	v_mov_b32_e32 v82, v81
	s_branch .LBB0_333

; template <int MODE> ...
;     ...
;         if (t >= act0 && t < act0 + actn) {
;         const LAS unsigned char* Sl = ring + ((t + base) % 3) * SLOT;
; #pragma unroll
;         for (int hf = 0; hf < NH; ++hf) {
;             if (MODE == 1) { const int ks = ktok0 + 64 * t + 32 * hf;
;                 if (ks + 31 < qtok0 - 128 || ks > qtok0 + 31 + 128) continue; }
;             bf16x8 kf[2][2][2];
; #pragma unroll
;             for (int jj = 0; jj < 2; ++jj)
; #pragma unroll
;                 for (int kt = 0; kt < 2; ++kt)
; #pragma unroll
;                     for (int ks = 0; ks < 2; ++ks) kf[jj][kt][ks] = *(const LAS bf16x8*)(Sl + kad[jj][ks] + (32 * hf + 16 * kt) * 128);
;             f32x4 bb[2][2];
; #pragma unroll
;             for (int jj = 0; jj < 2; ++jj) { const LAS f32x4* bl = bcp + ((MODE == 0) ? (dr0 + t - act0) * 8 : 16 * t + 8 * hf) + bofs[jj];
; #pragma unroll
;                 for (int kt = 0; kt < 2; ++kt) bb[jj][kt] = bl[4 * kt]; }
;             s16x4 vlo[2][4], vhi[2][4];
; #pragma unroll
;             for (int jj = 0; jj < 2; ++jj)
; #pragma unroll
;                 for (int dt = 0; dt < 4; ++dt) { const LAS unsigned char* vp = Sl + vad[jj] + (32 * hf) * 128 + ((dt ^ sv) << 5);
;                     vlo[jj][dt] = __builtin_bit_cast(s16x4, __builtin_amdgcn_ds_read_tr16_b64_v4i16((LAS s16x4*)(vp)));
;                     vhi[jj][dt] = __builtin_bit_cast(s16x4, __builtin_amdgcn_ds_read_tr16_b64_v4i16((LAS s16x4*)(vp + 2048))); }
;             __builtin_amdgcn_sched_barrier(0);
;             f32x4 s[2][2];
; #pragma unroll
;             for (int jj = 0; jj < 2; ++jj)
; #pragma unroll
;                 for (int kt = 0; kt < 2; ++kt) { f32x4 a = (MODE == 0) ? bb[jj][kt] + mneg[jj][kt] : bb[jj][kt];
;                     a = __builtin_amdgcn_mfma_f32_16x16x32_bf16(kf[jj][kt][0], qf[jj][0], a, 0, 0, 0);
;                     s[jj][kt] = __builtin_amdgcn_mfma_f32_16x16x32_bf16(kf[jj][kt][1], qf[jj][1], a, 0, 0, 0); }
;             u32x4 pw[2];
; #pragma unroll
;             for (int jj = 0; jj < 2; ++jj) {
;     ...
;     { const GAS bf16_t* qs = nQ ? (const GAS bf16_t*)nQ : (const GAS bf16_t*)proj + (size_t)qtok0 * NIN + qcol;
; #pragma unroll
;       for (int jj = 0; jj < 2; ++jj)
; #pragma unroll
;           for (int ks = 0; ks < 2; ++ks) qn[jj][ks] = *(const GAS bf16x8*)(qs + (size_t)(16 * jj) * NIN + 32 * ks + qoff); }
.LBB0_356:
	v_lshl_add_u64 v[6:7], v[66:67], 1, s[38:39]
	global_load_dwordx4 v[2:5], v[6:7], off
	global_load_dwordx4 v[10:13], v[6:7], off offset:64
	v_add_co_u32_e32 v6, vcc, 0x12000, v6
	s_cmp_lt_i32 s5, 1
	s_nop 0
	v_addc_co_u32_e32 v7, vcc, 0, v7, vcc
	global_load_dwordx4 v[14:17], v[6:7], off
	s_nop 0
	global_load_dwordx4 v[6:9], v[6:7], off offset:64
	s_cbranch_scc1 .LBB0_361
	s_mul_i32 s0, s22, 0x600
	s_add_i32 s27, s0, 0
	s_add_i32 s0, s26, s86
	s_mul_hi_i32 s14, s0, 0x55555556
	s_lshr_b32 s15, s14, 31
	s_add_i32 s14, s14, s15
	s_mul_i32 s14, s14, 3
	s_sub_i32 s0, s0, s14
	s_lshl_b32 s30, s26, 6
	s_lshl_b32 s0, s0, 14
	s_add_i32 s14, s30, s24
	s_add_i32 s27, s27, 0x10000
	s_add_i32 s0, s0, 0
	s_lshl_b32 s26, s26, 8
	s_or_b32 s15, s14, 31
	s_add_i32 s31, s25, 0xffffff80
	s_cmp_lt_i32 s15, s31
	s_cselect_b64 s[38:39], -1, 0
	s_addk_i32 s25, 0x9f
	s_cmp_gt_i32 s14, s25
	s_cselect_b64 s[40:41], -1, 0
	s_or_b64 s[38:39], s[38:39], s[40:41]
	v_add_u32_e32 v100, s0, v70
	v_add_u32_e32 v99, s0, v71
	v_add3_u32 v66, v72, v73, s0
	s_movk_i32 s0, 0x60
	s_and_b64 vcc, exec, s[38:39]
	v_add_u32_e32 v98, v66, v74
	v_xad_u32 v97, v74, 32, v66
	v_xad_u32 v0, v74, 64, v66
	v_xad_u32 v96, v74, s0, v66
	s_cbranch_vccnz .LBB0_359
	s_add_i32 s0, s27, s26
	v_lshl_add_u32 v66, v93, 4, s0
	ds_read_b128 v[102:105], v100
	ds_read_b128 v[106:109], v100 offset:2048
	ds_read_b128 v[110:113], v99
	ds_read_b128 v[118:121], v99 offset:2048
	ds_read_b128 v[122:125], v66
	ds_read_b128 v[126:129], v66 offset:64
	v_lshl_add_u32 v66, v94, 4, s0
	ds_read_b128 v[130:133], v66
	ds_read_b128 v[134:137], v66 offset:64
	ds_read_b64_tr_b16 v[78:79], v98 offset:8192
	ds_read_b64_tr_b16 v[80:81], v98 offset:10240
	ds_read_b64_tr_b16 v[74:75], v97 offset:8192
	ds_read_b64_tr_b16 v[76:77], v97 offset:10240
	ds_read_b64_tr_b16 v[70:71], v0 offset:8192
	ds_read_b64_tr_b16 v[72:73], v0 offset:10240
	ds_read_b64_tr_b16 v[66:67], v96 offset:8192
	ds_read_b64_tr_b16 v[68:69], v96 offset:10240
	s_waitcnt lgkmcnt(11)
	v_mfma_f32_16x16x32_bf16 v[122:125], v[102:105], v[30:33], v[122:125]
	s_waitcnt lgkmcnt(10)
	v_mfma_f32_16x16x32_bf16 v[126:129], v[106:109], v[30:33], v[126:129]
	s_waitcnt lgkmcnt(9)
	v_mfma_f32_16x16x32_bf16 v[102:105], v[102:105], v[22:25], v[130:133]
	s_waitcnt lgkmcnt(8)
	v_mfma_f32_16x16x32_bf16 v[106:109], v[106:109], v[22:25], v[134:137]
	v_mfma_f32_16x16x32_bf16 v[102:105], v[110:113], v[18:21], v[102:105]
	v_mfma_f32_16x16x32_bf16 v[106:109], v[118:121], v[18:21], v[106:109]
	v_mfma_f32_16x16x32_bf16 v[122:125], v[110:113], v[26:29], v[122:125]
	s_nop 5
	v_maximum3_f32 v111, v102, v103, v104
	v_maximum3_f32 v113, v105, v106, v107
	v_maximum3_f32 v115, v108, v109, v109
	v_mfma_f32_16x16x32_bf16 v[126:129], v[118:121], v[26:29], v[126:129]
	v_maximum3_f32 v111, v111, v113, v115
	v_maximum3_f32 v83, v122, v123, v124
	v_mov_b32_e32 v113, v111
	s_nop 1
	v_permlane16_swap_b32_e32 v111, v113
	v_maximum3_f32 v111, v111, v113, v113
	s_nop 0
	v_maximum3_f32 v84, v125, v126, v127
	v_maximum3_f32 v85, v128, v129, v129
	v_maximum3_f32 v83, v83, v84, v85
	v_mov_b32_e32 v84, v83
	s_nop 1
	v_permlane16_swap_b32_e32 v83, v84
	v_maximum3_f32 v83, v83, v84, v84
	v_mov_b32_e32 v113, v111
	v_mov_b32_e32 v84, v83
	s_nop 0
	v_permlane32_swap_b32_e32 v111, v113
	v_permlane32_swap_b32_e32 v83, v84
	v_maximum3_f32 v117, v95, v111, v113
	v_maximum3_f32 v101, v82, v83, v84
	v_sub_f32_e32 v102, v102, v117
	v_sub_f32_e32 v83, v122, v101
	v_exp_f32_e32 v111, v102
	v_sub_f32_e32 v102, v103, v117
	v_exp_f32_e32 v110, v83
	v_sub_f32_e32 v83, v123, v101
	v_exp_f32_e32 v113, v102
	v_sub_f32_e32 v102, v104, v117
	v_exp_f32_e32 v112, v83
	v_sub_f32_e32 v83, v124, v101
	v_exp_f32_e32 v115, v102
	v_sub_f32_e32 v102, v105, v117
	v_exp_f32_e32 v114, v83
	v_sub_f32_e32 v83, v125, v101
	v_exp_f32_e32 v119, v102
	v_sub_f32_e32 v102, v106, v117
	v_exp_f32_e32 v118, v83
	v_sub_f32_e32 v83, v126, v101
	v_exp_f32_e32 v121, v102
	v_sub_f32_e32 v102, v107, v117
	v_sub_f32_e32 v82, v82, v101
	v_exp_f32_e32 v120, v83
	v_sub_f32_e32 v83, v127, v101
	v_exp_f32_e32 v123, v102
	v_sub_f32_e32 v102, v108, v117
	v_exp_f32_e32 v122, v83
	v_sub_f32_e32 v83, v128, v101
	v_exp_f32_e32 v128, v82
	v_pk_add_f32 v[130:131], v[110:111], 0 op_sel_hi:[1,0]
	v_exp_f32_e32 v125, v102
	v_sub_f32_e32 v102, v109, v117
	v_exp_f32_e32 v127, v102
	v_pk_add_f32 v[102:103], v[112:113], v[130:131]
	v_exp_f32_e32 v124, v83
	v_sub_f32_e32 v83, v129, v101
	v_pk_add_f32 v[102:103], v[114:115], v[102:103]
	v_exp_f32_e32 v126, v83
	v_sub_f32_e32 v95, v95, v117
	v_pk_add_f32 v[102:103], v[118:119], v[102:103]
	v_pk_mul_f32 v[52:53], v[52:53], v[128:129] op_sel_hi:[1,0]
	v_pk_mul_f32 v[50:51], v[50:51], v[128:129] op_sel_hi:[1,0]
	v_pk_mul_f32 v[56:57], v[56:57], v[128:129] op_sel_hi:[1,0]
	v_pk_mul_f32 v[54:55], v[54:55], v[128:129] op_sel_hi:[1,0]
	v_pk_mul_f32 v[60:61], v[60:61], v[128:129] op_sel_hi:[1,0]
	v_pk_mul_f32 v[58:59], v[58:59], v[128:129] op_sel_hi:[1,0]
	v_pk_mul_f32 v[64:65], v[64:65], v[128:129] op_sel_hi:[1,0]
	v_pk_mul_f32 v[62:63], v[62:63], v[128:129] op_sel_hi:[1,0]
	v_exp_f32_e32 v129, v95
	v_pk_add_f32 v[102:103], v[120:121], v[102:103]
	v_cvt_pk_bf16_f32 v82, v110, v112
	v_pk_add_f32 v[102:103], v[122:123], v[102:103]
	v_cvt_pk_bf16_f32 v83, v114, v118
	v_pk_add_f32 v[102:103], v[124:125], v[102:103]
	v_cvt_pk_bf16_f32 v84, v120, v122
	v_pk_add_f32 v[102:103], v[126:127], v[102:103]
	v_cvt_pk_bf16_f32 v85, v124, v126
	v_pk_fma_f32 v[88:89], v[88:89], v[128:129], v[102:103]
	v_mov_b32_e32 v102, v129
	v_pk_mul_f32 v[36:37], v[36:37], v[102:103] op_sel_hi:[1,0]
	v_pk_mul_f32 v[34:35], v[34:35], v[102:103] op_sel_hi:[1,0]
	v_pk_mul_f32 v[40:41], v[40:41], v[102:103] op_sel_hi:[1,0]
	v_pk_mul_f32 v[38:39], v[38:39], v[102:103] op_sel_hi:[1,0]
	v_pk_mul_f32 v[44:45], v[44:45], v[102:103] op_sel_hi:[1,0]
	v_pk_mul_f32 v[42:43], v[42:43], v[102:103] op_sel_hi:[1,0]
	v_pk_mul_f32 v[48:49], v[48:49], v[102:103] op_sel_hi:[1,0]
	v_pk_mul_f32 v[46:47], v[46:47], v[102:103] op_sel_hi:[1,0]
	v_cvt_pk_bf16_f32 v102, v111, v113
	v_cvt_pk_bf16_f32 v103, v115, v119
	v_cvt_pk_bf16_f32 v104, v121, v123
	v_cvt_pk_bf16_f32 v105, v125, v127
	s_setprio 1
	s_waitcnt lgkmcnt(6)
	v_mfma_f32_16x16x32_bf16 v[50:53], v[78:81], v[82:85], v[50:53]
	s_waitcnt lgkmcnt(4)
	v_mfma_f32_16x16x32_bf16 v[54:57], v[74:77], v[82:85], v[54:57]
	s_waitcnt lgkmcnt(2)
	v_mfma_f32_16x16x32_bf16 v[58:61], v[70:73], v[82:85], v[58:61]
	s_waitcnt lgkmcnt(0)
	v_mfma_f32_16x16x32_bf16 v[62:65], v[66:69], v[82:85], v[62:65]
	v_mfma_f32_16x16x32_bf16 v[34:37], v[78:81], v[102:105], v[34:37]
	v_mfma_f32_16x16x32_bf16 v[38:41], v[74:77], v[102:105], v[38:41]
	v_mfma_f32_16x16x32_bf16 v[42:45], v[70:73], v[102:105], v[42:45]
	v_mfma_f32_16x16x32_bf16 v[46:49], v[66:69], v[102:105], v[46:49]
	s_setprio 0
	v_mov_b32_e32 v82, v101
	v_mov_b32_e32 v95, v117
; template <int MODE> ...
;     ...
;         for (int hf = 0; hf < NH; ++hf) {
;             if (MODE == 1) { const int ks = ktok0 + 64 * t + 32 * hf;
;                 if (ks + 31 < qtok0 - 128 || ks > qtok0 + 31 + 128) continue; }
;             bf16x8 kf[2][2][2];
; #pragma unroll
;             for (int jj = 0; jj < 2; ++jj)
; #pragma unroll
;                 for (int kt = 0; kt < 2; ++kt)
; #pragma unroll
;                     for (int ks = 0; ks < 2; ++ks) kf[jj][kt][ks] = *(const LAS bf16x8*)(Sl + kad[jj][ks] + (32 * hf + 16 * kt) * 128);
;             f32x4 bb[2][2];
; #pragma unroll
;             for (int jj = 0; jj < 2; ++jj) { const LAS f32x4* bl = bcp + ((MODE == 0) ? (dr0 + t - act0) * 8 : 16 * t + 8 * hf) + bofs[jj];
; #pragma unroll
;                 for (int kt = 0; kt < 2; ++kt) bb[jj][kt] = bl[4 * kt]; }
;             s16x4 vlo[2][4], vhi[2][4];
; #pragma unroll
;             for (int jj = 0; jj < 2; ++jj)
; #pragma unroll
;                 for (int dt = 0; dt < 4; ++dt) { const LAS unsigned char* vp = Sl + vad[jj] + (32 * hf) * 128 + ((dt ^ sv) << 5);
;                     vlo[jj][dt] = __builtin_bit_cast(s16x4, __builtin_amdgcn_ds_read_tr16_b64_v4i16((LAS s16x4*)(vp)));
;                     vhi[jj][dt] = __builtin_bit_cast(s16x4, __builtin_amdgcn_ds_read_tr16_b64_v4i16((LAS s16x4*)(vp + 2048))); }
;             __builtin_amdgcn_sched_barrier(0);
;             f32x4 s[2][2];
; #pragma unroll
;             for (int jj = 0; jj < 2; ++jj)
; #pragma unroll
;                 for (int kt = 0; kt < 2; ++kt) { f32x4 a = (MODE == 0) ? bb[jj][kt] + mneg[jj][kt] : bb[jj][kt];
;                     a = __builtin_amdgcn_mfma_f32_16x16x32_bf16(kf[jj][kt][0], qf[jj][0], a, 0, 0, 0);
;                     s[jj][kt] = __builtin_amdgcn_mfma_f32_16x16x32_bf16(kf[jj][kt][1], qf[jj][1], a, 0, 0, 0); }
;             u32x4 pw[2];
; #pragma unroll
;             for (int jj = 0; jj < 2; ++jj) {
;                 const float tm = vmax3(vmax3(s[jj][0][0], s[jj][0][1], s[jj][0][2]), vmax3(s[jj][0][3], s[jj][1][0], s[jj][1][1]), vmax3(s[jj][1][2], s[jj][1][3], s[jj][1][3]));
;                 const float mn = quad_max3(mrun[jj], tm);
;                 const float alpha = __builtin_amdgcn_exp2f(mrun[jj] - mn);
;                 mrun[jj] = mn;
;                 float rsum = 0.f;
; #pragma unroll
;                 for (int kt = 0; kt < 2; ++kt)
; #pragma unroll
.LBB0_359:
	s_or_b32 s0, s30, 32
	s_add_i32 s0, s0, s24
	s_or_b32 s14, s0, 31
	s_cmp_lt_i32 s14, s31
	s_cselect_b64 s[30:31], -1, 0
	s_cmp_gt_i32 s0, s25
	s_cselect_b64 s[24:25], -1, 0
	s_or_b64 s[24:25], s[30:31], s[24:25]
	s_and_b64 vcc, exec, s[24:25]
	s_cbranch_vccnz .LBB0_361
	s_add_i32 s27, s27, s26
	v_lshl_add_u32 v83, v93, 4, s27
	ds_read_b128 v[66:69], v100 offset:4096
	ds_read_b128 v[70:73], v100 offset:6144
	ds_read_b128 v[74:77], v99 offset:4096
	ds_read_b128 v[78:81], v99 offset:6144
	ds_read_b128 v[100:103], v83 offset:128
	ds_read_b128 v[104:107], v83 offset:192
	v_lshl_add_u32 v83, v94, 4, s27
	ds_read_b128 v[108:111], v83 offset:128
	ds_read_b128 v[112:115], v83 offset:192
	ds_read_b64_tr_b16 v[118:119], v98 offset:12288
	ds_read_b64_tr_b16 v[120:121], v98 offset:14336
	ds_read_b64_tr_b16 v[122:123], v97 offset:12288
	ds_read_b64_tr_b16 v[124:125], v97 offset:14336
	ds_read_b64_tr_b16 v[126:127], v0 offset:12288
	ds_read_b64_tr_b16 v[128:129], v0 offset:14336
	ds_read_b64_tr_b16 v[130:131], v96 offset:12288
	ds_read_b64_tr_b16 v[132:133], v96 offset:14336
	s_waitcnt lgkmcnt(11)
	v_mfma_f32_16x16x32_bf16 v[96:99], v[66:69], v[30:33], v[100:103]
	s_waitcnt lgkmcnt(10)
	v_mfma_f32_16x16x32_bf16 v[30:33], v[70:73], v[30:33], v[104:107]
	v_mfma_f32_16x16x32_bf16 v[96:99], v[74:77], v[26:29], v[96:99]
	v_mfma_f32_16x16x32_bf16 v[26:29], v[78:81], v[26:29], v[30:33]
	s_nop 6
	v_maximum3_f32 v0, v96, v97, v98
	v_maximum3_f32 v30, v99, v26, v27
	v_maximum3_f32 v31, v28, v29, v29
	v_maximum3_f32 v0, v0, v30, v31
	v_mov_b32_e32 v30, v0
	s_nop 1
	v_permlane16_swap_b32_e32 v0, v30
	v_maximum3_f32 v0, v0, v30, v30
	v_mov_b32_e32 v30, v0
	s_nop 1
	v_permlane32_swap_b32_e32 v0, v30
	v_maximum3_f32 v0, v82, v0, v30
	s_waitcnt lgkmcnt(9)
	v_mfma_f32_16x16x32_bf16 v[30:33], v[66:69], v[22:25], v[108:111]
	v_sub_f32_e32 v83, v82, v0
	v_sub_f32_e32 v66, v97, v0
	v_exp_f32_e32 v84, v66
	s_waitcnt lgkmcnt(8)
	v_mfma_f32_16x16x32_bf16 v[22:25], v[70:73], v[22:25], v[112:115]
	v_sub_f32_e32 v66, v98, v0
	v_sub_f32_e32 v82, v96, v0
	v_sub_f32_e32 v26, v26, v0
	v_mfma_f32_16x16x32_bf16 v[30:33], v[74:77], v[18:21], v[30:33]
	v_exp_f32_e32 v74, v66
	v_sub_f32_e32 v66, v99, v0
	v_exp_f32_e32 v82, v82
	v_mfma_f32_16x16x32_bf16 v[18:21], v[78:81], v[18:21], v[22:25]
	v_exp_f32_e32 v78, v83
	v_exp_f32_e32 v70, v66
	v_exp_f32_e32 v72, v26
	v_sub_f32_e32 v22, v27, v0
	v_exp_f32_e32 v76, v22
	v_sub_f32_e32 v22, v28, v0
	v_sub_f32_e32 v0, v29, v0
	v_exp_f32_e32 v80, v22
	v_exp_f32_e32 v94, v0
	v_pk_mul_f32 v[22:23], v[50:51], v[78:79] op_sel_hi:[1,0]
	v_maximum3_f32 v0, v30, v31, v32
	v_maximum3_f32 v50, v33, v18, v19
	v_maximum3_f32 v51, v20, v21, v21
	v_maximum3_f32 v0, v0, v50, v51
	v_mov_b32_e32 v50, v0
	s_nop 1
	v_permlane16_swap_b32_e32 v0, v50
	v_maximum3_f32 v0, v0, v50, v50
	v_mov_b32_e32 v50, v0
	s_nop 1
	v_permlane32_swap_b32_e32 v0, v50
	v_maximum3_f32 v0, v95, v0, v50
	v_sub_f32_e32 v30, v30, v0
	v_exp_f32_e32 v83, v30
	v_sub_f32_e32 v30, v31, v0
	v_exp_f32_e32 v85, v30
	v_sub_f32_e32 v30, v32, v0
	v_sub_f32_e32 v18, v18, v0
	v_exp_f32_e32 v75, v30
	v_sub_f32_e32 v30, v33, v0
	v_exp_f32_e32 v73, v18
	v_sub_f32_e32 v18, v19, v0
	v_sub_f32_e32 v50, v95, v0
	v_exp_f32_e32 v71, v30
	v_exp_f32_e32 v77, v18
	v_sub_f32_e32 v18, v20, v0
	v_pk_mul_f32 v[24:25], v[52:53], v[78:79] op_sel_hi:[1,0]
	v_pk_mul_f32 v[28:29], v[56:57], v[78:79] op_sel_hi:[1,0]
	v_pk_mul_f32 v[26:27], v[54:55], v[78:79] op_sel_hi:[1,0]
	v_pk_mul_f32 v[60:61], v[60:61], v[78:79] op_sel_hi:[1,0]
	v_pk_mul_f32 v[58:59], v[58:59], v[78:79] op_sel_hi:[1,0]
	v_pk_mul_f32 v[64:65], v[64:65], v[78:79] op_sel_hi:[1,0]
	v_pk_mul_f32 v[62:63], v[62:63], v[78:79] op_sel_hi:[1,0]
	v_exp_f32_e32 v81, v18
	v_sub_f32_e32 v0, v21, v0
	v_exp_f32_e32 v79, v50
	v_pk_add_f32 v[18:19], v[82:83], 0 op_sel_hi:[1,0]
	v_exp_f32_e32 v95, v0
	v_pk_add_f32 v[18:19], v[84:85], v[18:19]
	v_cvt_pk_bf16_f32 v66, v82, v84
	v_pk_add_f32 v[18:19], v[74:75], v[18:19]
	v_cvt_pk_bf16_f32 v67, v74, v70
	v_pk_add_f32 v[18:19], v[70:71], v[18:19]
	v_cvt_pk_bf16_f32 v68, v72, v76
	v_cvt_pk_bf16_f32 v69, v80, v94
	v_pk_add_f32 v[18:19], v[72:73], v[18:19]
	v_mov_b32_e32 v0, v79
	s_setprio 1
	s_waitcnt lgkmcnt(6)
	v_mfma_f32_16x16x32_bf16 v[50:53], v[118:121], v[66:69], v[22:25]
	v_pk_mul_f32 v[20:21], v[36:37], v[0:1] op_sel_hi:[1,0]
	s_waitcnt lgkmcnt(4)
	v_mfma_f32_16x16x32_bf16 v[54:57], v[122:125], v[66:69], v[26:29]
	v_cvt_pk_bf16_f32 v22, v83, v85
	v_cvt_pk_bf16_f32 v23, v75, v71
	v_cvt_pk_bf16_f32 v24, v73, v77
	v_pk_add_f32 v[26:27], v[76:77], v[18:19]
	v_pk_mul_f32 v[18:19], v[34:35], v[0:1] op_sel_hi:[1,0]
	v_cvt_pk_bf16_f32 v25, v81, v95
	s_waitcnt lgkmcnt(2)
	v_mfma_f32_16x16x32_bf16 v[58:61], v[126:129], v[66:69], v[58:61]
	v_pk_add_f32 v[26:27], v[80:81], v[26:27]
	v_pk_add_f32 v[26:27], v[94:95], v[26:27]
	v_mfma_f32_16x16x32_bf16 v[34:37], v[118:121], v[22:25], v[18:21]
	v_fma_f32 v88, v88, v78, v26
	v_fma_f32 v89, v89, v79, v27
	s_nop 0
	v_pk_mul_f32 v[20:21], v[40:41], v[0:1] op_sel_hi:[1,0]
	v_pk_mul_f32 v[18:19], v[38:39], v[0:1] op_sel_hi:[1,0]
	s_waitcnt lgkmcnt(0)
	v_mfma_f32_16x16x32_bf16 v[62:65], v[130:133], v[66:69], v[62:65]
	v_mfma_f32_16x16x32_bf16 v[38:41], v[122:125], v[22:25], v[18:21]
	s_setprio 0
	s_nop 2
	v_pk_mul_f32 v[20:21], v[44:45], v[0:1] op_sel_hi:[1,0]
	v_pk_mul_f32 v[18:19], v[42:43], v[0:1] op_sel_hi:[1,0]
	s_nop 1
	v_mfma_f32_16x16x32_bf16 v[42:45], v[126:129], v[22:25], v[18:21]
	s_nop 2
	v_pk_mul_f32 v[20:21], v[48:49], v[0:1] op_sel_hi:[1,0]
	v_pk_mul_f32 v[18:19], v[46:47], v[0:1] op_sel_hi:[1,0]
	s_nop 1
	v_mfma_f32_16x16x32_bf16 v[46:49], v[130:133], v[22:25], v[18:21]
